# scan consumer: group-3 y transposes deferred into the next chunk's DPP gaps (exec-masked first store), v056 otherwise
# speedup vs baseline: 1.0119x; 1.0119x over previous
.Lscan_cons_chunk:
	v_cndmask_b32_e64 v2, v4, v5, s[42:43]
	v_add_lshl_u32 v2, v2, s80, 10
	v_mov_b32_e32 v3, v180
	s_add_i32 s28, s28, 0x10000
	v_lshl_add_u64 v[2:3], v[0:1], 0, v[2:3]
	v_add_u32_e32 v5, 64, v5
	v_subrev_u32_e32 v4, 64, v4
	s_waitcnt lgkmcnt(3)
	v_fma_mix_f32 v12, v6, v20, v180 op_sel_hi:[0,1,0]
	v_fma_mix_f32 v12, v7, v20, v12 op_sel:[0,1,0] op_sel_hi:[0,1,0]
	v_fma_mix_f32 v12, v8, v21, v12 op_sel_hi:[0,1,0]
	v_fma_mix_f32 v12, v9, v21, v12 op_sel:[0,1,0] op_sel_hi:[0,1,0]
	s_nop 1
	v_add_f32_dpp v12, v12, v12 row_ror:1 row_mask:0xf bank_mask:0xf bound_ctrl:1
	s_nop 1
	v_add_f32_dpp v12, v12, v12 row_ror:2 row_mask:0xf bank_mask:0xf bound_ctrl:1
	v_pk_fma_f32 v[48:49], v[28:29], v[66:67], v[6:7] op_sel_hi:[1,0,1]
	v_pk_fma_f32 v[50:51], v[30:31], v[66:67], v[8:9] op_sel_hi:[1,0,1]
	v_add_f32_dpp v12, v12, v12 row_ror:4 row_mask:0xf bank_mask:0xf bound_ctrl:1
	v_add_f32_dpp v130, v130, v130 row_ror:8 row_mask:0xf bank_mask:0xc
	v_add_f32_dpp v130, v122, v122 row_ror:8 row_mask:0xf bank_mask:0x3
	v_add_f32_dpp v131, v131, v131 row_ror:8 row_mask:0xf bank_mask:0xc
	v_add_f32_dpp v12, v12, v12 row_ror:8 row_mask:0xf bank_mask:0xf bound_ctrl:1
	v_pk_fma_f32 v[6:7], v[24:25], v[12:13], v[48:49] op_sel_hi:[1,0,1] neg_lo:[1,0,0] neg_hi:[1,0,0]
	v_pk_fma_f32 v[8:9], v[26:27], v[12:13], v[50:51] op_sel_hi:[1,0,1] neg_lo:[1,0,0] neg_hi:[1,0,0]
	ds_read_b128 v[88:91], v10 offset:2304
	ds_read_b128 v[96:99], v10 offset:2816
	ds_read_b128 v[92:95], v10 offset:2560
	s_waitcnt lgkmcnt(3)
	v_fma_mix_f32 v12, v6, v36, v180 op_sel_hi:[0,1,0]
	v_fma_mix_f32 v12, v7, v36, v12 op_sel:[0,1,0] op_sel_hi:[0,1,0]
	v_fma_mix_f32 v12, v8, v37, v12 op_sel_hi:[0,1,0]
	v_fma_mix_f32 v12, v9, v37, v12 op_sel:[0,1,0] op_sel_hi:[0,1,0]
	v_fma_mix_f32 v52, v6, v22, v180 op_sel_hi:[0,1,0]
	v_fma_mix_f32 v52, v7, v22, v52 op_sel:[0,1,0] op_sel_hi:[0,1,0]
	v_add_f32_dpp v12, v12, v12 row_ror:1 row_mask:0xf bank_mask:0xf bound_ctrl:1
	v_fma_mix_f32 v52, v8, v23, v52 op_sel_hi:[0,1,0]
	v_fma_mix_f32 v52, v9, v23, v52 op_sel:[0,1,0] op_sel_hi:[0,1,0]
	v_add_f32_dpp v12, v12, v12 row_ror:2 row_mask:0xf bank_mask:0xf bound_ctrl:1
	v_pk_fma_f32 v[48:49], v[44:45], v[66:67], v[6:7] op_sel:[0,1,0]
	v_pk_fma_f32 v[50:51], v[46:47], v[66:67], v[8:9] op_sel:[0,1,0]
	v_add_f32_dpp v12, v12, v12 row_ror:4 row_mask:0xf bank_mask:0xf bound_ctrl:1
	v_add_f32_dpp v131, v123, v123 row_ror:8 row_mask:0xf bank_mask:0x3
	v_add_f32_dpp v132, v132, v132 row_ror:8 row_mask:0xf bank_mask:0xc
	v_add_f32_dpp v132, v124, v124 row_ror:8 row_mask:0xf bank_mask:0x3
	v_add_f32_dpp v12, v12, v12 row_ror:8 row_mask:0xf bank_mask:0xf bound_ctrl:1
	v_pk_fma_f32 v[6:7], v[40:41], v[12:13], v[48:49] op_sel_hi:[1,0,1] neg_lo:[1,0,0] neg_hi:[1,0,0]
	v_pk_fma_f32 v[8:9], v[42:43], v[12:13], v[50:51] op_sel_hi:[1,0,1] neg_lo:[1,0,0] neg_hi:[1,0,0]
	ds_read_b128 v[110:113], v10 offset:3328
	ds_read_b128 v[106:109], v10 offset:3072
	ds_read_b128 v[118:121], v10 offset:3840
	ds_read_b128 v[114:117], v10 offset:3584
	ds_read_b128 v[70:73], v11 offset:256
	s_waitcnt lgkmcnt(5)
	v_fma_mix_f32 v12, v6, v88, v180 op_sel_hi:[0,1,0]
	v_fma_mix_f32 v12, v7, v88, v12 op_sel:[0,1,0] op_sel_hi:[0,1,0]
	v_fma_mix_f32 v12, v8, v89, v12 op_sel_hi:[0,1,0]
	v_fma_mix_f32 v12, v9, v89, v12 op_sel:[0,1,0] op_sel_hi:[0,1,0]
	v_fma_mix_f32 v53, v6, v38, v180 op_sel_hi:[0,1,0]
	v_fma_mix_f32 v53, v7, v38, v53 op_sel:[0,1,0] op_sel_hi:[0,1,0]
	v_add_f32_dpp v12, v12, v12 row_ror:1 row_mask:0xf bank_mask:0xf bound_ctrl:1
	v_fma_mix_f32 v53, v8, v39, v53 op_sel_hi:[0,1,0]
	v_fma_mix_f32 v53, v9, v39, v53 op_sel:[0,1,0] op_sel_hi:[0,1,0]
	v_add_f32_dpp v12, v12, v12 row_ror:2 row_mask:0xf bank_mask:0xf bound_ctrl:1
	v_pk_fma_f32 v[48:49], v[96:97], v[68:69], v[6:7] op_sel_hi:[1,0,1]
	v_pk_fma_f32 v[50:51], v[98:99], v[68:69], v[8:9] op_sel_hi:[1,0,1]
	v_add_f32_dpp v12, v12, v12 row_ror:4 row_mask:0xf bank_mask:0xf bound_ctrl:1
	v_add_f32_dpp v133, v133, v133 row_ror:8 row_mask:0xf bank_mask:0xc
	v_add_f32_dpp v133, v125, v125 row_ror:8 row_mask:0xf bank_mask:0x3
	v_add_f32_dpp v134, v134, v134 row_ror:8 row_mask:0xf bank_mask:0xc
	v_add_f32_dpp v12, v12, v12 row_ror:8 row_mask:0xf bank_mask:0xf bound_ctrl:1
	v_pk_fma_f32 v[6:7], v[92:93], v[12:13], v[48:49] op_sel_hi:[1,0,1] neg_lo:[1,0,0] neg_hi:[1,0,0]
	v_pk_fma_f32 v[8:9], v[94:95], v[12:13], v[50:51] op_sel_hi:[1,0,1] neg_lo:[1,0,0] neg_hi:[1,0,0]
	ds_read_b128 v[20:23], v10 offset:4352
	ds_read_b128 v[28:31], v10 offset:4864
	ds_read_b128 v[24:27], v10 offset:4608
	s_waitcnt lgkmcnt(4)
	v_fma_mix_f32 v12, v6, v110, v180 op_sel_hi:[0,1,0]
	v_fma_mix_f32 v12, v7, v110, v12 op_sel:[0,1,0] op_sel_hi:[0,1,0]
	v_fma_mix_f32 v12, v8, v111, v12 op_sel_hi:[0,1,0]
	v_fma_mix_f32 v12, v9, v111, v12 op_sel:[0,1,0] op_sel_hi:[0,1,0]
	v_fma_mix_f32 v54, v6, v90, v180 op_sel_hi:[0,1,0]
	v_fma_mix_f32 v54, v7, v90, v54 op_sel:[0,1,0] op_sel_hi:[0,1,0]
	v_add_f32_dpp v12, v12, v12 row_ror:1 row_mask:0xf bank_mask:0xf bound_ctrl:1
	v_fma_mix_f32 v54, v8, v91, v54 op_sel_hi:[0,1,0]
	v_fma_mix_f32 v54, v9, v91, v54 op_sel:[0,1,0] op_sel_hi:[0,1,0]
	v_add_f32_dpp v12, v12, v12 row_ror:2 row_mask:0xf bank_mask:0xf bound_ctrl:1
	v_pk_fma_f32 v[48:49], v[118:119], v[68:69], v[6:7] op_sel:[0,1,0]
	v_pk_fma_f32 v[50:51], v[120:121], v[68:69], v[8:9] op_sel:[0,1,0]
	v_add_f32_dpp v12, v12, v12 row_ror:4 row_mask:0xf bank_mask:0xf bound_ctrl:1
	v_add_f32_dpp v134, v126, v126 row_ror:8 row_mask:0xf bank_mask:0x3
	v_add_f32_dpp v135, v135, v135 row_ror:8 row_mask:0xf bank_mask:0xc
	v_add_f32_dpp v135, v127, v127 row_ror:8 row_mask:0xf bank_mask:0x3
	v_add_f32_dpp v12, v12, v12 row_ror:8 row_mask:0xf bank_mask:0xf bound_ctrl:1
	v_pk_fma_f32 v[6:7], v[114:115], v[12:13], v[48:49] op_sel_hi:[1,0,1] neg_lo:[1,0,0] neg_hi:[1,0,0]
	v_pk_fma_f32 v[8:9], v[116:117], v[12:13], v[50:51] op_sel_hi:[1,0,1] neg_lo:[1,0,0] neg_hi:[1,0,0]
	v_pk_mul_f32 v[6:7], v[6:7], v[106:107]
	v_pk_mul_f32 v[8:9], v[8:9], v[108:109]
	ds_read_b128 v[36:39], v10 offset:5376
	ds_read_b128 v[44:47], v10 offset:5888
	ds_read_b128 v[40:43], v10 offset:5632
	s_waitcnt lgkmcnt(3)
	v_fma_mix_f32 v12, v6, v20, v180 op_sel_hi:[0,1,0]
	v_fma_mix_f32 v12, v7, v20, v12 op_sel:[0,1,0] op_sel_hi:[0,1,0]
	v_fma_mix_f32 v12, v8, v21, v12 op_sel_hi:[0,1,0]
	v_fma_mix_f32 v12, v9, v21, v12 op_sel:[0,1,0] op_sel_hi:[0,1,0]
	v_fma_mix_f32 v55, v6, v112, v180 op_sel_hi:[0,1,0]
	v_fma_mix_f32 v55, v7, v112, v55 op_sel:[0,1,0] op_sel_hi:[0,1,0]
	v_add_f32_dpp v12, v12, v12 row_ror:1 row_mask:0xf bank_mask:0xf bound_ctrl:1
	v_fma_mix_f32 v55, v8, v113, v55 op_sel_hi:[0,1,0]
	v_fma_mix_f32 v55, v9, v113, v55 op_sel:[0,1,0] op_sel_hi:[0,1,0]
	v_add_f32_dpp v12, v12, v12 row_ror:2 row_mask:0xf bank_mask:0xf bound_ctrl:1
	v_pk_fma_f32 v[48:49], v[28:29], v[70:71], v[6:7] op_sel_hi:[1,0,1]
	v_pk_fma_f32 v[50:51], v[30:31], v[70:71], v[8:9] op_sel_hi:[1,0,1]
	v_add_f32_dpp v12, v12, v12 row_ror:4 row_mask:0xf bank_mask:0xf bound_ctrl:1
	v_add_f32_dpp v136, v136, v136 row_ror:8 row_mask:0xf bank_mask:0xc
	v_add_f32_dpp v136, v128, v128 row_ror:8 row_mask:0xf bank_mask:0x3
	v_add_f32_dpp v12, v12, v12 row_ror:8 row_mask:0xf bank_mask:0xf bound_ctrl:1
	v_pk_fma_f32 v[6:7], v[24:25], v[12:13], v[48:49] op_sel_hi:[1,0,1] neg_lo:[1,0,0] neg_hi:[1,0,0]
	v_pk_fma_f32 v[8:9], v[26:27], v[12:13], v[50:51] op_sel_hi:[1,0,1] neg_lo:[1,0,0] neg_hi:[1,0,0]
	ds_read_b128 v[88:91], v10 offset:6400
	ds_read_b128 v[96:99], v10 offset:6912
	ds_read_b128 v[92:95], v10 offset:6656
	s_waitcnt lgkmcnt(3)
	v_fma_mix_f32 v12, v6, v36, v180 op_sel_hi:[0,1,0]
	v_fma_mix_f32 v12, v7, v36, v12 op_sel:[0,1,0] op_sel_hi:[0,1,0]
	v_fma_mix_f32 v12, v8, v37, v12 op_sel_hi:[0,1,0]
	v_fma_mix_f32 v12, v9, v37, v12 op_sel:[0,1,0] op_sel_hi:[0,1,0]
	v_fma_mix_f32 v56, v6, v22, v180 op_sel_hi:[0,1,0]
	v_fma_mix_f32 v56, v7, v22, v56 op_sel:[0,1,0] op_sel_hi:[0,1,0]
	v_add_f32_dpp v12, v12, v12 row_ror:1 row_mask:0xf bank_mask:0xf bound_ctrl:1
	v_fma_mix_f32 v56, v8, v23, v56 op_sel_hi:[0,1,0]
	v_fma_mix_f32 v56, v9, v23, v56 op_sel:[0,1,0] op_sel_hi:[0,1,0]
	v_add_f32_dpp v12, v12, v12 row_ror:2 row_mask:0xf bank_mask:0xf bound_ctrl:1
	v_pk_fma_f32 v[48:49], v[44:45], v[70:71], v[6:7] op_sel:[0,1,0]
	v_pk_fma_f32 v[50:51], v[46:47], v[70:71], v[8:9] op_sel:[0,1,0]
	v_add_f32_dpp v12, v12, v12 row_ror:4 row_mask:0xf bank_mask:0xf bound_ctrl:1
	v_add_f32_dpp v137, v137, v137 row_ror:8 row_mask:0xf bank_mask:0xc
	v_add_f32_dpp v137, v129, v129 row_ror:8 row_mask:0xf bank_mask:0x3
	v_add_f32_dpp v12, v12, v12 row_ror:8 row_mask:0xf bank_mask:0xf bound_ctrl:1
	v_pk_fma_f32 v[6:7], v[40:41], v[12:13], v[48:49] op_sel_hi:[1,0,1] neg_lo:[1,0,0] neg_hi:[1,0,0]
	v_pk_fma_f32 v[8:9], v[42:43], v[12:13], v[50:51] op_sel_hi:[1,0,1] neg_lo:[1,0,0] neg_hi:[1,0,0]
	ds_read_b128 v[110:113], v10 offset:7424
	ds_read_b128 v[106:109], v10 offset:7168
	ds_read_b128 v[118:121], v10 offset:7936
	ds_read_b128 v[114:117], v10 offset:7680
	ds_read_b128 v[66:69], v11 offset:512
	s_waitcnt lgkmcnt(5)
	v_fma_mix_f32 v12, v6, v88, v180 op_sel_hi:[0,1,0]
	v_fma_mix_f32 v12, v7, v88, v12 op_sel:[0,1,0] op_sel_hi:[0,1,0]
	v_fma_mix_f32 v12, v8, v89, v12 op_sel_hi:[0,1,0]
	v_fma_mix_f32 v12, v9, v89, v12 op_sel:[0,1,0] op_sel_hi:[0,1,0]
	v_fma_mix_f32 v57, v6, v38, v180 op_sel_hi:[0,1,0]
	v_fma_mix_f32 v57, v7, v38, v57 op_sel:[0,1,0] op_sel_hi:[0,1,0]
	v_add_f32_dpp v12, v12, v12 row_ror:1 row_mask:0xf bank_mask:0xf bound_ctrl:1
	v_fma_mix_f32 v57, v8, v39, v57 op_sel_hi:[0,1,0]
	v_fma_mix_f32 v57, v9, v39, v57 op_sel:[0,1,0] op_sel_hi:[0,1,0]
	v_add_f32_dpp v12, v12, v12 row_ror:2 row_mask:0xf bank_mask:0xf bound_ctrl:1
	v_pk_fma_f32 v[48:49], v[96:97], v[72:73], v[6:7] op_sel_hi:[1,0,1]
	v_pk_fma_f32 v[50:51], v[98:99], v[72:73], v[8:9] op_sel_hi:[1,0,1]
	v_add_f32_dpp v12, v12, v12 row_ror:4 row_mask:0xf bank_mask:0xf bound_ctrl:1
	v_add_f32_dpp v134, v134, v134 row_ror:4 row_mask:0xf bank_mask:0xa
	v_add_f32_dpp v134, v130, v130 row_ror:12 row_mask:0xf bank_mask:0x5
	v_add_f32_dpp v135, v135, v135 row_ror:4 row_mask:0xf bank_mask:0xa
	v_add_f32_dpp v12, v12, v12 row_ror:8 row_mask:0xf bank_mask:0xf bound_ctrl:1
	v_pk_fma_f32 v[6:7], v[92:93], v[12:13], v[48:49] op_sel_hi:[1,0,1] neg_lo:[1,0,0] neg_hi:[1,0,0]
	v_pk_fma_f32 v[8:9], v[94:95], v[12:13], v[50:51] op_sel_hi:[1,0,1] neg_lo:[1,0,0] neg_hi:[1,0,0]
	ds_read_b128 v[20:23], v10 offset:8448
	ds_read_b128 v[28:31], v10 offset:8960
	ds_read_b128 v[24:27], v10 offset:8704
	s_waitcnt lgkmcnt(4)
	v_fma_mix_f32 v12, v6, v110, v180 op_sel_hi:[0,1,0]
	v_fma_mix_f32 v12, v7, v110, v12 op_sel:[0,1,0] op_sel_hi:[0,1,0]
	v_fma_mix_f32 v12, v8, v111, v12 op_sel_hi:[0,1,0]
	v_fma_mix_f32 v12, v9, v111, v12 op_sel:[0,1,0] op_sel_hi:[0,1,0]
	v_fma_mix_f32 v81, v6, v90, v180 op_sel_hi:[0,1,0]
	v_fma_mix_f32 v81, v7, v90, v81 op_sel:[0,1,0] op_sel_hi:[0,1,0]
	v_add_f32_dpp v12, v12, v12 row_ror:1 row_mask:0xf bank_mask:0xf bound_ctrl:1
	v_fma_mix_f32 v81, v8, v91, v81 op_sel_hi:[0,1,0]
	v_fma_mix_f32 v81, v9, v91, v81 op_sel:[0,1,0] op_sel_hi:[0,1,0]
	v_add_f32_dpp v12, v12, v12 row_ror:2 row_mask:0xf bank_mask:0xf bound_ctrl:1
	v_pk_fma_f32 v[48:49], v[118:119], v[72:73], v[6:7] op_sel:[0,1,0]
	v_pk_fma_f32 v[50:51], v[120:121], v[72:73], v[8:9] op_sel:[0,1,0]
	v_add_f32_dpp v12, v12, v12 row_ror:4 row_mask:0xf bank_mask:0xf bound_ctrl:1
	v_add_f32_dpp v135, v131, v131 row_ror:12 row_mask:0xf bank_mask:0x5
	v_add_f32_dpp v136, v136, v136 row_ror:4 row_mask:0xf bank_mask:0xa
	v_add_f32_dpp v136, v132, v132 row_ror:12 row_mask:0xf bank_mask:0x5
	v_add_f32_dpp v12, v12, v12 row_ror:8 row_mask:0xf bank_mask:0xf bound_ctrl:1
	v_pk_fma_f32 v[6:7], v[114:115], v[12:13], v[48:49] op_sel_hi:[1,0,1] neg_lo:[1,0,0] neg_hi:[1,0,0]
	v_pk_fma_f32 v[8:9], v[116:117], v[12:13], v[50:51] op_sel_hi:[1,0,1] neg_lo:[1,0,0] neg_hi:[1,0,0]
	v_pk_mul_f32 v[6:7], v[6:7], v[106:107]
	v_pk_mul_f32 v[8:9], v[8:9], v[108:109]
	ds_read_b128 v[36:39], v10 offset:9472
	ds_read_b128 v[44:47], v10 offset:9984
	ds_read_b128 v[40:43], v10 offset:9728
	s_waitcnt lgkmcnt(3)
	v_fma_mix_f32 v12, v6, v20, v180 op_sel_hi:[0,1,0]
	v_fma_mix_f32 v12, v7, v20, v12 op_sel:[0,1,0] op_sel_hi:[0,1,0]
	v_fma_mix_f32 v12, v8, v21, v12 op_sel_hi:[0,1,0]
	v_fma_mix_f32 v12, v9, v21, v12 op_sel:[0,1,0] op_sel_hi:[0,1,0]
	v_fma_mix_f32 v82, v6, v112, v180 op_sel_hi:[0,1,0]
	v_fma_mix_f32 v82, v7, v112, v82 op_sel:[0,1,0] op_sel_hi:[0,1,0]
	v_add_f32_dpp v12, v12, v12 row_ror:1 row_mask:0xf bank_mask:0xf bound_ctrl:1
	v_fma_mix_f32 v82, v8, v113, v82 op_sel_hi:[0,1,0]
	v_fma_mix_f32 v82, v9, v113, v82 op_sel:[0,1,0] op_sel_hi:[0,1,0]
	v_add_f32_dpp v12, v12, v12 row_ror:2 row_mask:0xf bank_mask:0xf bound_ctrl:1
	v_pk_fma_f32 v[48:49], v[28:29], v[66:67], v[6:7] op_sel_hi:[1,0,1]
	v_pk_fma_f32 v[50:51], v[30:31], v[66:67], v[8:9] op_sel_hi:[1,0,1]
	v_add_f32_dpp v12, v12, v12 row_ror:4 row_mask:0xf bank_mask:0xf bound_ctrl:1
	v_add_f32_dpp v137, v137, v137 row_ror:4 row_mask:0xf bank_mask:0xa
	v_add_f32_dpp v137, v133, v133 row_ror:12 row_mask:0xf bank_mask:0x5
	v_add_f32_dpp v12, v12, v12 row_ror:8 row_mask:0xf bank_mask:0xf bound_ctrl:1
	v_pk_fma_f32 v[6:7], v[24:25], v[12:13], v[48:49] op_sel_hi:[1,0,1] neg_lo:[1,0,0] neg_hi:[1,0,0]
	v_pk_fma_f32 v[8:9], v[26:27], v[12:13], v[50:51] op_sel_hi:[1,0,1] neg_lo:[1,0,0] neg_hi:[1,0,0]
	ds_read_b128 v[88:91], v10 offset:10496
	ds_read_b128 v[96:99], v10 offset:11008
	ds_read_b128 v[92:95], v10 offset:10752
	s_waitcnt lgkmcnt(3)
	v_fma_mix_f32 v12, v6, v36, v180 op_sel_hi:[0,1,0]
	v_fma_mix_f32 v12, v7, v36, v12 op_sel:[0,1,0] op_sel_hi:[0,1,0]
	v_fma_mix_f32 v12, v8, v37, v12 op_sel_hi:[0,1,0]
	v_fma_mix_f32 v12, v9, v37, v12 op_sel:[0,1,0] op_sel_hi:[0,1,0]
	v_fma_mix_f32 v83, v6, v22, v180 op_sel_hi:[0,1,0]
	v_fma_mix_f32 v83, v7, v22, v83 op_sel:[0,1,0] op_sel_hi:[0,1,0]
	v_add_f32_dpp v12, v12, v12 row_ror:1 row_mask:0xf bank_mask:0xf bound_ctrl:1
	v_fma_mix_f32 v83, v8, v23, v83 op_sel_hi:[0,1,0]
	v_fma_mix_f32 v83, v9, v23, v83 op_sel:[0,1,0] op_sel_hi:[0,1,0]
	v_add_f32_dpp v12, v12, v12 row_ror:2 row_mask:0xf bank_mask:0xf bound_ctrl:1
	v_pk_fma_f32 v[48:49], v[44:45], v[66:67], v[6:7] op_sel:[0,1,0]
	v_pk_fma_f32 v[50:51], v[46:47], v[66:67], v[8:9] op_sel:[0,1,0]
	v_add_f32_dpp v12, v12, v12 row_ror:4 row_mask:0xf bank_mask:0xf bound_ctrl:1
	v_cndmask_b32_e64 v62, v136, v134, s[38:39]
	v_cndmask_b32_e64 v63, v134, v136, s[38:39]
	v_add_f32_dpp v12, v12, v12 row_ror:8 row_mask:0xf bank_mask:0xf bound_ctrl:1
	v_pk_fma_f32 v[6:7], v[40:41], v[12:13], v[48:49] op_sel_hi:[1,0,1] neg_lo:[1,0,0] neg_hi:[1,0,0]
	v_pk_fma_f32 v[8:9], v[42:43], v[12:13], v[50:51] op_sel_hi:[1,0,1] neg_lo:[1,0,0] neg_hi:[1,0,0]
	ds_read_b128 v[110:113], v10 offset:11520
	ds_read_b128 v[106:109], v10 offset:11264
	ds_read_b128 v[118:121], v10 offset:12032
	ds_read_b128 v[114:117], v10 offset:11776
	ds_read_b128 v[70:73], v11 offset:768
	s_waitcnt lgkmcnt(5)
	v_fma_mix_f32 v12, v6, v88, v180 op_sel_hi:[0,1,0]
	v_fma_mix_f32 v12, v7, v88, v12 op_sel:[0,1,0] op_sel_hi:[0,1,0]
	v_fma_mix_f32 v12, v8, v89, v12 op_sel_hi:[0,1,0]
	v_fma_mix_f32 v12, v9, v89, v12 op_sel:[0,1,0] op_sel_hi:[0,1,0]
	v_fma_mix_f32 v100, v6, v38, v180 op_sel_hi:[0,1,0]
	v_fma_mix_f32 v100, v7, v38, v100 op_sel:[0,1,0] op_sel_hi:[0,1,0]
	v_add_f32_dpp v12, v12, v12 row_ror:1 row_mask:0xf bank_mask:0xf bound_ctrl:1
	v_fma_mix_f32 v100, v8, v39, v100 op_sel_hi:[0,1,0]
	v_fma_mix_f32 v100, v9, v39, v100 op_sel:[0,1,0] op_sel_hi:[0,1,0]
	v_add_f32_dpp v12, v12, v12 row_ror:2 row_mask:0xf bank_mask:0xf bound_ctrl:1
	v_pk_fma_f32 v[48:49], v[96:97], v[68:69], v[6:7] op_sel_hi:[1,0,1]
	v_pk_fma_f32 v[50:51], v[98:99], v[68:69], v[8:9] op_sel_hi:[1,0,1]
	v_add_f32_dpp v12, v12, v12 row_ror:4 row_mask:0xf bank_mask:0xf bound_ctrl:1
	v_cndmask_b32_e64 v64, v137, v135, s[38:39]
	v_cndmask_b32_e64 v65, v135, v137, s[38:39]
	v_add_f32_dpp v12, v12, v12 row_ror:8 row_mask:0xf bank_mask:0xf bound_ctrl:1
	v_pk_fma_f32 v[6:7], v[92:93], v[12:13], v[48:49] op_sel_hi:[1,0,1] neg_lo:[1,0,0] neg_hi:[1,0,0]
	v_pk_fma_f32 v[8:9], v[94:95], v[12:13], v[50:51] op_sel_hi:[1,0,1] neg_lo:[1,0,0] neg_hi:[1,0,0]
	ds_read_b128 v[20:23], v10 offset:12544
	ds_read_b128 v[28:31], v10 offset:13056
	ds_read_b128 v[24:27], v10 offset:12800
	s_waitcnt lgkmcnt(4)
	v_fma_mix_f32 v12, v6, v110, v180 op_sel_hi:[0,1,0]
	v_fma_mix_f32 v12, v7, v110, v12 op_sel:[0,1,0] op_sel_hi:[0,1,0]
	v_fma_mix_f32 v12, v8, v111, v12 op_sel_hi:[0,1,0]
	v_fma_mix_f32 v12, v9, v111, v12 op_sel:[0,1,0] op_sel_hi:[0,1,0]
	v_fma_mix_f32 v101, v6, v90, v180 op_sel_hi:[0,1,0]
	v_fma_mix_f32 v101, v7, v90, v101 op_sel:[0,1,0] op_sel_hi:[0,1,0]
	v_add_f32_dpp v12, v12, v12 row_ror:1 row_mask:0xf bank_mask:0xf bound_ctrl:1
	v_fma_mix_f32 v101, v8, v91, v101 op_sel_hi:[0,1,0]
	v_fma_mix_f32 v101, v9, v91, v101 op_sel:[0,1,0] op_sel_hi:[0,1,0]
	v_add_f32_dpp v12, v12, v12 row_ror:2 row_mask:0xf bank_mask:0xf bound_ctrl:1
	v_pk_fma_f32 v[48:49], v[118:119], v[68:69], v[6:7] op_sel:[0,1,0]
	v_pk_fma_f32 v[50:51], v[120:121], v[68:69], v[8:9] op_sel:[0,1,0]
	v_add_f32_dpp v12, v12, v12 row_ror:4 row_mask:0xf bank_mask:0xf bound_ctrl:1
	v_add_f32_dpp v62, v63, v62 quad_perm:[2,3,0,1] row_mask:0xf bank_mask:0xf bound_ctrl:1
	v_add_f32_dpp v63, v65, v64 quad_perm:[2,3,0,1] row_mask:0xf bank_mask:0xf bound_ctrl:1
	v_add_f32_dpp v12, v12, v12 row_ror:8 row_mask:0xf bank_mask:0xf bound_ctrl:1
	v_pk_fma_f32 v[6:7], v[114:115], v[12:13], v[48:49] op_sel_hi:[1,0,1] neg_lo:[1,0,0] neg_hi:[1,0,0]
	v_pk_fma_f32 v[8:9], v[116:117], v[12:13], v[50:51] op_sel_hi:[1,0,1] neg_lo:[1,0,0] neg_hi:[1,0,0]
	v_pk_mul_f32 v[6:7], v[6:7], v[106:107]
	v_pk_mul_f32 v[8:9], v[8:9], v[108:109]
	ds_read_b128 v[36:39], v10 offset:13568
	ds_read_b128 v[44:47], v10 offset:14080
	ds_read_b128 v[40:43], v10 offset:13824
	s_waitcnt lgkmcnt(3)
	v_fma_mix_f32 v12, v6, v20, v180 op_sel_hi:[0,1,0]
	v_fma_mix_f32 v12, v7, v20, v12 op_sel:[0,1,0] op_sel_hi:[0,1,0]
	v_fma_mix_f32 v12, v8, v21, v12 op_sel_hi:[0,1,0]
	v_fma_mix_f32 v12, v9, v21, v12 op_sel:[0,1,0] op_sel_hi:[0,1,0]
	v_fma_mix_f32 v102, v6, v112, v180 op_sel_hi:[0,1,0]
	v_fma_mix_f32 v102, v7, v112, v102 op_sel:[0,1,0] op_sel_hi:[0,1,0]
	v_add_f32_dpp v12, v12, v12 row_ror:1 row_mask:0xf bank_mask:0xf bound_ctrl:1
	v_fma_mix_f32 v102, v8, v113, v102 op_sel_hi:[0,1,0]
	v_fma_mix_f32 v102, v9, v113, v102 op_sel:[0,1,0] op_sel_hi:[0,1,0]
	v_add_f32_dpp v12, v12, v12 row_ror:2 row_mask:0xf bank_mask:0xf bound_ctrl:1
	v_pk_fma_f32 v[48:49], v[28:29], v[70:71], v[6:7] op_sel_hi:[1,0,1]
	v_pk_fma_f32 v[50:51], v[30:31], v[70:71], v[8:9] op_sel_hi:[1,0,1]
	v_add_f32_dpp v12, v12, v12 row_ror:4 row_mask:0xf bank_mask:0xf bound_ctrl:1
	v_cndmask_b32_e64 v65, v63, v62, s[40:41]
	v_cndmask_b32_e64 v62, v62, v63, s[40:41]
	v_add_f32_dpp v12, v12, v12 row_ror:8 row_mask:0xf bank_mask:0xf bound_ctrl:1
	v_pk_fma_f32 v[6:7], v[24:25], v[12:13], v[48:49] op_sel_hi:[1,0,1] neg_lo:[1,0,0] neg_hi:[1,0,0]
	v_pk_fma_f32 v[8:9], v[26:27], v[12:13], v[50:51] op_sel_hi:[1,0,1] neg_lo:[1,0,0] neg_hi:[1,0,0]
	ds_read_b128 v[88:91], v10 offset:14592
	ds_read_b128 v[96:99], v10 offset:15104
	ds_read_b128 v[92:95], v10 offset:14848
	s_waitcnt lgkmcnt(3)
	v_fma_mix_f32 v12, v6, v36, v180 op_sel_hi:[0,1,0]
	v_fma_mix_f32 v12, v7, v36, v12 op_sel:[0,1,0] op_sel_hi:[0,1,0]
	v_fma_mix_f32 v12, v8, v37, v12 op_sel_hi:[0,1,0]
	v_fma_mix_f32 v12, v9, v37, v12 op_sel:[0,1,0] op_sel_hi:[0,1,0]
	v_fma_mix_f32 v103, v6, v22, v180 op_sel_hi:[0,1,0]
	v_fma_mix_f32 v103, v7, v22, v103 op_sel:[0,1,0] op_sel_hi:[0,1,0]
	v_add_f32_dpp v12, v12, v12 row_ror:1 row_mask:0xf bank_mask:0xf bound_ctrl:1
	v_fma_mix_f32 v103, v8, v23, v103 op_sel_hi:[0,1,0]
	v_fma_mix_f32 v103, v9, v23, v103 op_sel:[0,1,0] op_sel_hi:[0,1,0]
	v_add_f32_dpp v12, v12, v12 row_ror:2 row_mask:0xf bank_mask:0xf bound_ctrl:1
	v_pk_fma_f32 v[48:49], v[44:45], v[70:71], v[6:7] op_sel:[0,1,0]
	v_pk_fma_f32 v[50:51], v[46:47], v[70:71], v[8:9] op_sel:[0,1,0]
	v_add_f32_dpp v12, v12, v12 row_ror:4 row_mask:0xf bank_mask:0xf bound_ctrl:1
	v_add_f32_dpp v62, v62, v65 quad_perm:[1,0,3,2] row_mask:0xf bank_mask:0xf bound_ctrl:1
	v_cvt_pk_bf16_f32 v62, v62, v62
	v_add_f32_dpp v12, v12, v12 row_ror:8 row_mask:0xf bank_mask:0xf bound_ctrl:1
	v_pk_fma_f32 v[6:7], v[40:41], v[12:13], v[48:49] op_sel_hi:[1,0,1] neg_lo:[1,0,0] neg_hi:[1,0,0]
	v_pk_fma_f32 v[8:9], v[42:43], v[12:13], v[50:51] op_sel_hi:[1,0,1] neg_lo:[1,0,0] neg_hi:[1,0,0]
	ds_read_b128 v[110:113], v10 offset:15616
	ds_read_b128 v[106:109], v10 offset:15360
	ds_read_b128 v[118:121], v10 offset:16128
	ds_read_b128 v[114:117], v10 offset:15872
	ds_read_b128 v[66:69], v11 offset:1024
	s_waitcnt lgkmcnt(5)
	v_fma_mix_f32 v12, v6, v88, v180 op_sel_hi:[0,1,0]
	v_fma_mix_f32 v12, v7, v88, v12 op_sel:[0,1,0] op_sel_hi:[0,1,0]
	v_fma_mix_f32 v12, v8, v89, v12 op_sel_hi:[0,1,0]
	v_fma_mix_f32 v12, v9, v89, v12 op_sel:[0,1,0] op_sel_hi:[0,1,0]
	v_fma_mix_f32 v104, v6, v38, v180 op_sel_hi:[0,1,0]
	v_fma_mix_f32 v104, v7, v38, v104 op_sel:[0,1,0] op_sel_hi:[0,1,0]
	v_add_f32_dpp v12, v12, v12 row_ror:1 row_mask:0xf bank_mask:0xf bound_ctrl:1
	v_fma_mix_f32 v104, v8, v39, v104 op_sel_hi:[0,1,0]
	v_fma_mix_f32 v104, v9, v39, v104 op_sel:[0,1,0] op_sel_hi:[0,1,0]
	v_add_f32_dpp v12, v12, v12 row_ror:2 row_mask:0xf bank_mask:0xf bound_ctrl:1
	v_pk_fma_f32 v[48:49], v[96:97], v[72:73], v[6:7] op_sel_hi:[1,0,1]
	v_pk_fma_f32 v[50:51], v[98:99], v[72:73], v[8:9] op_sel_hi:[1,0,1]
	v_add_f32_dpp v12, v12, v12 row_ror:4 row_mask:0xf bank_mask:0xf bound_ctrl:1
	s_mov_b64 exec, s[100:101]
	global_store_short v[170:171], v62, off
	s_mov_b64 exec, -1
	v_add_f32_dpp v12, v12, v12 row_ror:8 row_mask:0xf bank_mask:0xf bound_ctrl:1
	v_pk_fma_f32 v[6:7], v[92:93], v[12:13], v[48:49] op_sel_hi:[1,0,1] neg_lo:[1,0,0] neg_hi:[1,0,0]
	v_pk_fma_f32 v[8:9], v[94:95], v[12:13], v[50:51] op_sel_hi:[1,0,1] neg_lo:[1,0,0] neg_hi:[1,0,0]
	ds_read_b128 v[20:23], v10 offset:16640
	ds_read_b128 v[28:31], v10 offset:17152
	ds_read_b128 v[24:27], v10 offset:16896
	s_waitcnt lgkmcnt(4)
	v_fma_mix_f32 v12, v6, v110, v180 op_sel_hi:[0,1,0]
	v_fma_mix_f32 v12, v7, v110, v12 op_sel:[0,1,0] op_sel_hi:[0,1,0]
	v_fma_mix_f32 v12, v8, v111, v12 op_sel_hi:[0,1,0]
	v_fma_mix_f32 v12, v9, v111, v12 op_sel:[0,1,0] op_sel_hi:[0,1,0]
	v_fma_mix_f32 v105, v6, v90, v180 op_sel_hi:[0,1,0]
	v_fma_mix_f32 v105, v7, v90, v105 op_sel:[0,1,0] op_sel_hi:[0,1,0]
	v_add_f32_dpp v12, v12, v12 row_ror:1 row_mask:0xf bank_mask:0xf bound_ctrl:1
	v_fma_mix_f32 v105, v8, v91, v105 op_sel_hi:[0,1,0]
	v_fma_mix_f32 v105, v9, v91, v105 op_sel:[0,1,0] op_sel_hi:[0,1,0]
	v_add_f32_dpp v12, v12, v12 row_ror:2 row_mask:0xf bank_mask:0xf bound_ctrl:1
	v_pk_fma_f32 v[48:49], v[118:119], v[72:73], v[6:7] op_sel:[0,1,0]
	v_pk_fma_f32 v[50:51], v[120:121], v[72:73], v[8:9] op_sel:[0,1,0]
	v_add_f32_dpp v12, v12, v12 row_ror:4 row_mask:0xf bank_mask:0xf bound_ctrl:1
	s_nop 1
	v_add_f32_dpp v12, v12, v12 row_ror:8 row_mask:0xf bank_mask:0xf bound_ctrl:1
	v_pk_fma_f32 v[6:7], v[114:115], v[12:13], v[48:49] op_sel_hi:[1,0,1] neg_lo:[1,0,0] neg_hi:[1,0,0]
	v_pk_fma_f32 v[8:9], v[116:117], v[12:13], v[50:51] op_sel_hi:[1,0,1] neg_lo:[1,0,0] neg_hi:[1,0,0]
	v_pk_mul_f32 v[6:7], v[6:7], v[106:107]
	v_pk_mul_f32 v[8:9], v[8:9], v[108:109]
	ds_read_b128 v[36:39], v10 offset:17664
	ds_read_b128 v[44:47], v10 offset:18176
	ds_read_b128 v[40:43], v10 offset:17920
	s_waitcnt lgkmcnt(3)
	v_fma_mix_f32 v12, v6, v20, v180 op_sel_hi:[0,1,0]
	v_fma_mix_f32 v12, v7, v20, v12 op_sel:[0,1,0] op_sel_hi:[0,1,0]
	v_fma_mix_f32 v12, v8, v21, v12 op_sel_hi:[0,1,0]
	v_fma_mix_f32 v12, v9, v21, v12 op_sel:[0,1,0] op_sel_hi:[0,1,0]
	v_fma_mix_f32 v61, v6, v112, v180 op_sel_hi:[0,1,0]
	v_fma_mix_f32 v61, v7, v112, v61 op_sel:[0,1,0] op_sel_hi:[0,1,0]
	v_add_f32_dpp v12, v12, v12 row_ror:1 row_mask:0xf bank_mask:0xf bound_ctrl:1
	v_fma_mix_f32 v61, v8, v113, v61 op_sel_hi:[0,1,0]
	v_fma_mix_f32 v61, v9, v113, v61 op_sel:[0,1,0] op_sel_hi:[0,1,0]
	v_add_f32_dpp v12, v12, v12 row_ror:2 row_mask:0xf bank_mask:0xf bound_ctrl:1
	v_pk_fma_f32 v[48:49], v[28:29], v[66:67], v[6:7] op_sel_hi:[1,0,1]
	v_pk_fma_f32 v[50:51], v[30:31], v[66:67], v[8:9] op_sel_hi:[1,0,1]
	v_add_f32_dpp v12, v12, v12 row_ror:4 row_mask:0xf bank_mask:0xf bound_ctrl:1
	s_nop 1
	v_add_f32_dpp v12, v12, v12 row_ror:8 row_mask:0xf bank_mask:0xf bound_ctrl:1
	v_pk_fma_f32 v[6:7], v[24:25], v[12:13], v[48:49] op_sel_hi:[1,0,1] neg_lo:[1,0,0] neg_hi:[1,0,0]
	v_pk_fma_f32 v[8:9], v[26:27], v[12:13], v[50:51] op_sel_hi:[1,0,1] neg_lo:[1,0,0] neg_hi:[1,0,0]
	ds_read_b128 v[88:91], v10 offset:18688
	ds_read_b128 v[96:99], v10 offset:19200
	ds_read_b128 v[92:95], v10 offset:18944
	s_waitcnt lgkmcnt(3)
	v_fma_mix_f32 v12, v6, v36, v180 op_sel_hi:[0,1,0]
	v_fma_mix_f32 v12, v7, v36, v12 op_sel:[0,1,0] op_sel_hi:[0,1,0]
	v_fma_mix_f32 v12, v8, v37, v12 op_sel_hi:[0,1,0]
	v_fma_mix_f32 v12, v9, v37, v12 op_sel:[0,1,0] op_sel_hi:[0,1,0]
	v_fma_mix_f32 v122, v6, v22, v180 op_sel_hi:[0,1,0]
	v_fma_mix_f32 v122, v7, v22, v122 op_sel:[0,1,0] op_sel_hi:[0,1,0]
	v_add_f32_dpp v12, v12, v12 row_ror:1 row_mask:0xf bank_mask:0xf bound_ctrl:1
	v_fma_mix_f32 v122, v8, v23, v122 op_sel_hi:[0,1,0]
	v_fma_mix_f32 v122, v9, v23, v122 op_sel:[0,1,0] op_sel_hi:[0,1,0]
	v_add_f32_dpp v12, v12, v12 row_ror:2 row_mask:0xf bank_mask:0xf bound_ctrl:1
	v_pk_fma_f32 v[48:49], v[44:45], v[66:67], v[6:7] op_sel:[0,1,0]
	v_pk_fma_f32 v[50:51], v[46:47], v[66:67], v[8:9] op_sel:[0,1,0]
	v_add_f32_dpp v12, v12, v12 row_ror:4 row_mask:0xf bank_mask:0xf bound_ctrl:1
	v_add_f32_dpp v83, v83, v83 row_ror:8 row_mask:0xf bank_mask:0xc
	v_add_f32_dpp v83, v52, v52 row_ror:8 row_mask:0xf bank_mask:0x3
	v_add_f32_dpp v100, v100, v100 row_ror:8 row_mask:0xf bank_mask:0xc
	v_add_f32_dpp v12, v12, v12 row_ror:8 row_mask:0xf bank_mask:0xf bound_ctrl:1
	v_pk_fma_f32 v[6:7], v[40:41], v[12:13], v[48:49] op_sel_hi:[1,0,1] neg_lo:[1,0,0] neg_hi:[1,0,0]
	v_pk_fma_f32 v[8:9], v[42:43], v[12:13], v[50:51] op_sel_hi:[1,0,1] neg_lo:[1,0,0] neg_hi:[1,0,0]
	ds_read_b128 v[110:113], v10 offset:19712
	ds_read_b128 v[106:109], v10 offset:19456
	ds_read_b128 v[118:121], v10 offset:20224
	ds_read_b128 v[114:117], v10 offset:19968
	ds_read_b128 v[70:73], v11 offset:1280
	s_waitcnt lgkmcnt(5)
	v_fma_mix_f32 v12, v6, v88, v180 op_sel_hi:[0,1,0]
	v_fma_mix_f32 v12, v7, v88, v12 op_sel:[0,1,0] op_sel_hi:[0,1,0]
	v_fma_mix_f32 v12, v8, v89, v12 op_sel_hi:[0,1,0]
	v_fma_mix_f32 v12, v9, v89, v12 op_sel:[0,1,0] op_sel_hi:[0,1,0]
	v_fma_mix_f32 v123, v6, v38, v180 op_sel_hi:[0,1,0]
	v_fma_mix_f32 v123, v7, v38, v123 op_sel:[0,1,0] op_sel_hi:[0,1,0]
	v_add_f32_dpp v12, v12, v12 row_ror:1 row_mask:0xf bank_mask:0xf bound_ctrl:1
	v_fma_mix_f32 v123, v8, v39, v123 op_sel_hi:[0,1,0]
	v_fma_mix_f32 v123, v9, v39, v123 op_sel:[0,1,0] op_sel_hi:[0,1,0]
	v_add_f32_dpp v12, v12, v12 row_ror:2 row_mask:0xf bank_mask:0xf bound_ctrl:1
	v_pk_fma_f32 v[48:49], v[96:97], v[68:69], v[6:7] op_sel_hi:[1,0,1]
	v_pk_fma_f32 v[50:51], v[98:99], v[68:69], v[8:9] op_sel_hi:[1,0,1]
	v_add_f32_dpp v12, v12, v12 row_ror:4 row_mask:0xf bank_mask:0xf bound_ctrl:1
	v_add_f32_dpp v100, v53, v53 row_ror:8 row_mask:0xf bank_mask:0x3
	v_add_f32_dpp v101, v101, v101 row_ror:8 row_mask:0xf bank_mask:0xc
	v_add_f32_dpp v101, v54, v54 row_ror:8 row_mask:0xf bank_mask:0x3
	v_add_f32_dpp v12, v12, v12 row_ror:8 row_mask:0xf bank_mask:0xf bound_ctrl:1
	v_pk_fma_f32 v[6:7], v[92:93], v[12:13], v[48:49] op_sel_hi:[1,0,1] neg_lo:[1,0,0] neg_hi:[1,0,0]
	v_pk_fma_f32 v[8:9], v[94:95], v[12:13], v[50:51] op_sel_hi:[1,0,1] neg_lo:[1,0,0] neg_hi:[1,0,0]
	ds_read_b128 v[20:23], v10 offset:20736
	ds_read_b128 v[28:31], v10 offset:21248
	ds_read_b128 v[24:27], v10 offset:20992
	s_waitcnt lgkmcnt(4)
	v_fma_mix_f32 v12, v6, v110, v180 op_sel_hi:[0,1,0]
	v_fma_mix_f32 v12, v7, v110, v12 op_sel:[0,1,0] op_sel_hi:[0,1,0]
	v_fma_mix_f32 v12, v8, v111, v12 op_sel_hi:[0,1,0]
	v_fma_mix_f32 v12, v9, v111, v12 op_sel:[0,1,0] op_sel_hi:[0,1,0]
	v_fma_mix_f32 v124, v6, v90, v180 op_sel_hi:[0,1,0]
	v_fma_mix_f32 v124, v7, v90, v124 op_sel:[0,1,0] op_sel_hi:[0,1,0]
	v_add_f32_dpp v12, v12, v12 row_ror:1 row_mask:0xf bank_mask:0xf bound_ctrl:1
	v_fma_mix_f32 v124, v8, v91, v124 op_sel_hi:[0,1,0]
	v_fma_mix_f32 v124, v9, v91, v124 op_sel:[0,1,0] op_sel_hi:[0,1,0]
	v_add_f32_dpp v12, v12, v12 row_ror:2 row_mask:0xf bank_mask:0xf bound_ctrl:1
	v_pk_fma_f32 v[48:49], v[118:119], v[68:69], v[6:7] op_sel:[0,1,0]
	v_pk_fma_f32 v[50:51], v[120:121], v[68:69], v[8:9] op_sel:[0,1,0]
	v_add_f32_dpp v12, v12, v12 row_ror:4 row_mask:0xf bank_mask:0xf bound_ctrl:1
	v_add_f32_dpp v102, v102, v102 row_ror:8 row_mask:0xf bank_mask:0xc
	v_add_f32_dpp v102, v55, v55 row_ror:8 row_mask:0xf bank_mask:0x3
	v_add_f32_dpp v103, v103, v103 row_ror:8 row_mask:0xf bank_mask:0xc
	v_add_f32_dpp v12, v12, v12 row_ror:8 row_mask:0xf bank_mask:0xf bound_ctrl:1
	v_pk_fma_f32 v[6:7], v[114:115], v[12:13], v[48:49] op_sel_hi:[1,0,1] neg_lo:[1,0,0] neg_hi:[1,0,0]
	v_pk_fma_f32 v[8:9], v[116:117], v[12:13], v[50:51] op_sel_hi:[1,0,1] neg_lo:[1,0,0] neg_hi:[1,0,0]
	v_pk_mul_f32 v[6:7], v[6:7], v[106:107]
	v_pk_mul_f32 v[8:9], v[8:9], v[108:109]
	ds_read_b128 v[36:39], v10 offset:21760
	ds_read_b128 v[44:47], v10 offset:22272
	ds_read_b128 v[40:43], v10 offset:22016
	s_waitcnt lgkmcnt(3)
	v_fma_mix_f32 v12, v6, v20, v180 op_sel_hi:[0,1,0]
	v_fma_mix_f32 v12, v7, v20, v12 op_sel:[0,1,0] op_sel_hi:[0,1,0]
	v_fma_mix_f32 v12, v8, v21, v12 op_sel_hi:[0,1,0]
	v_fma_mix_f32 v12, v9, v21, v12 op_sel:[0,1,0] op_sel_hi:[0,1,0]
	v_fma_mix_f32 v125, v6, v112, v180 op_sel_hi:[0,1,0]
	v_fma_mix_f32 v125, v7, v112, v125 op_sel:[0,1,0] op_sel_hi:[0,1,0]
	v_add_f32_dpp v12, v12, v12 row_ror:1 row_mask:0xf bank_mask:0xf bound_ctrl:1
	v_fma_mix_f32 v125, v8, v113, v125 op_sel_hi:[0,1,0]
	v_fma_mix_f32 v125, v9, v113, v125 op_sel:[0,1,0] op_sel_hi:[0,1,0]
	v_add_f32_dpp v12, v12, v12 row_ror:2 row_mask:0xf bank_mask:0xf bound_ctrl:1
	v_pk_fma_f32 v[48:49], v[28:29], v[70:71], v[6:7] op_sel_hi:[1,0,1]
	v_pk_fma_f32 v[50:51], v[30:31], v[70:71], v[8:9] op_sel_hi:[1,0,1]
	v_add_f32_dpp v12, v12, v12 row_ror:4 row_mask:0xf bank_mask:0xf bound_ctrl:1
	v_add_f32_dpp v103, v56, v56 row_ror:8 row_mask:0xf bank_mask:0x3
	v_add_f32_dpp v104, v104, v104 row_ror:8 row_mask:0xf bank_mask:0xc
	v_add_f32_dpp v104, v57, v57 row_ror:8 row_mask:0xf bank_mask:0x3
	v_add_f32_dpp v12, v12, v12 row_ror:8 row_mask:0xf bank_mask:0xf bound_ctrl:1
	v_pk_fma_f32 v[6:7], v[24:25], v[12:13], v[48:49] op_sel_hi:[1,0,1] neg_lo:[1,0,0] neg_hi:[1,0,0]
	v_pk_fma_f32 v[8:9], v[26:27], v[12:13], v[50:51] op_sel_hi:[1,0,1] neg_lo:[1,0,0] neg_hi:[1,0,0]
	ds_read_b128 v[88:91], v10 offset:22784
	ds_read_b128 v[96:99], v10 offset:23296
	ds_read_b128 v[92:95], v10 offset:23040
	s_waitcnt lgkmcnt(3)
	v_fma_mix_f32 v12, v6, v36, v180 op_sel_hi:[0,1,0]
	v_fma_mix_f32 v12, v7, v36, v12 op_sel:[0,1,0] op_sel_hi:[0,1,0]
	v_fma_mix_f32 v12, v8, v37, v12 op_sel_hi:[0,1,0]
	v_fma_mix_f32 v12, v9, v37, v12 op_sel:[0,1,0] op_sel_hi:[0,1,0]
	v_fma_mix_f32 v126, v6, v22, v180 op_sel_hi:[0,1,0]
	v_fma_mix_f32 v126, v7, v22, v126 op_sel:[0,1,0] op_sel_hi:[0,1,0]
	v_add_f32_dpp v12, v12, v12 row_ror:1 row_mask:0xf bank_mask:0xf bound_ctrl:1
	v_fma_mix_f32 v126, v8, v23, v126 op_sel_hi:[0,1,0]
	v_fma_mix_f32 v126, v9, v23, v126 op_sel:[0,1,0] op_sel_hi:[0,1,0]
	v_add_f32_dpp v12, v12, v12 row_ror:2 row_mask:0xf bank_mask:0xf bound_ctrl:1
	v_pk_fma_f32 v[48:49], v[44:45], v[70:71], v[6:7] op_sel:[0,1,0]
	v_pk_fma_f32 v[50:51], v[46:47], v[70:71], v[8:9] op_sel:[0,1,0]
	v_add_f32_dpp v12, v12, v12 row_ror:4 row_mask:0xf bank_mask:0xf bound_ctrl:1
	v_add_f32_dpp v105, v105, v105 row_ror:8 row_mask:0xf bank_mask:0xc
	v_add_f32_dpp v105, v81, v81 row_ror:8 row_mask:0xf bank_mask:0x3
	v_add_f32_dpp v12, v12, v12 row_ror:8 row_mask:0xf bank_mask:0xf bound_ctrl:1
	v_pk_fma_f32 v[6:7], v[40:41], v[12:13], v[48:49] op_sel_hi:[1,0,1] neg_lo:[1,0,0] neg_hi:[1,0,0]
	v_pk_fma_f32 v[8:9], v[42:43], v[12:13], v[50:51] op_sel_hi:[1,0,1] neg_lo:[1,0,0] neg_hi:[1,0,0]
	ds_read_b128 v[110:113], v10 offset:23808
	ds_read_b128 v[106:109], v10 offset:23552
	ds_read_b128 v[118:121], v10 offset:24320
	ds_read_b128 v[114:117], v10 offset:24064
	ds_read_b128 v[66:69], v11 offset:1536
	s_waitcnt lgkmcnt(5)
	v_fma_mix_f32 v12, v6, v88, v180 op_sel_hi:[0,1,0]
	v_fma_mix_f32 v12, v7, v88, v12 op_sel:[0,1,0] op_sel_hi:[0,1,0]
	v_fma_mix_f32 v12, v8, v89, v12 op_sel_hi:[0,1,0]
	v_fma_mix_f32 v12, v9, v89, v12 op_sel:[0,1,0] op_sel_hi:[0,1,0]
	v_fma_mix_f32 v127, v6, v38, v180 op_sel_hi:[0,1,0]
	v_fma_mix_f32 v127, v7, v38, v127 op_sel:[0,1,0] op_sel_hi:[0,1,0]
	v_add_f32_dpp v12, v12, v12 row_ror:1 row_mask:0xf bank_mask:0xf bound_ctrl:1
	v_fma_mix_f32 v127, v8, v39, v127 op_sel_hi:[0,1,0]
	v_fma_mix_f32 v127, v9, v39, v127 op_sel:[0,1,0] op_sel_hi:[0,1,0]
	v_add_f32_dpp v12, v12, v12 row_ror:2 row_mask:0xf bank_mask:0xf bound_ctrl:1
	v_pk_fma_f32 v[48:49], v[96:97], v[72:73], v[6:7] op_sel_hi:[1,0,1]
	v_pk_fma_f32 v[50:51], v[98:99], v[72:73], v[8:9] op_sel_hi:[1,0,1]
	v_add_f32_dpp v12, v12, v12 row_ror:4 row_mask:0xf bank_mask:0xf bound_ctrl:1
	v_add_f32_dpp v61, v61, v61 row_ror:8 row_mask:0xf bank_mask:0xc
	v_add_f32_dpp v61, v82, v82 row_ror:8 row_mask:0xf bank_mask:0x3
	v_add_f32_dpp v12, v12, v12 row_ror:8 row_mask:0xf bank_mask:0xf bound_ctrl:1
	v_pk_fma_f32 v[6:7], v[92:93], v[12:13], v[48:49] op_sel_hi:[1,0,1] neg_lo:[1,0,0] neg_hi:[1,0,0]
	v_pk_fma_f32 v[8:9], v[94:95], v[12:13], v[50:51] op_sel_hi:[1,0,1] neg_lo:[1,0,0] neg_hi:[1,0,0]
	ds_read_b128 v[20:23], v10 offset:24832
	ds_read_b128 v[28:31], v10 offset:25344
	ds_read_b128 v[24:27], v10 offset:25088
	s_waitcnt lgkmcnt(4)
	v_fma_mix_f32 v12, v6, v110, v180 op_sel_hi:[0,1,0]
	v_fma_mix_f32 v12, v7, v110, v12 op_sel:[0,1,0] op_sel_hi:[0,1,0]
	v_fma_mix_f32 v12, v8, v111, v12 op_sel_hi:[0,1,0]
	v_fma_mix_f32 v12, v9, v111, v12 op_sel:[0,1,0] op_sel_hi:[0,1,0]
	v_fma_mix_f32 v128, v6, v90, v180 op_sel_hi:[0,1,0]
	v_fma_mix_f32 v128, v7, v90, v128 op_sel:[0,1,0] op_sel_hi:[0,1,0]
	v_add_f32_dpp v12, v12, v12 row_ror:1 row_mask:0xf bank_mask:0xf bound_ctrl:1
	v_fma_mix_f32 v128, v8, v91, v128 op_sel_hi:[0,1,0]
	v_fma_mix_f32 v128, v9, v91, v128 op_sel:[0,1,0] op_sel_hi:[0,1,0]
	v_add_f32_dpp v12, v12, v12 row_ror:2 row_mask:0xf bank_mask:0xf bound_ctrl:1
	v_pk_fma_f32 v[48:49], v[118:119], v[72:73], v[6:7] op_sel:[0,1,0]
	v_pk_fma_f32 v[50:51], v[120:121], v[72:73], v[8:9] op_sel:[0,1,0]
	v_add_f32_dpp v12, v12, v12 row_ror:4 row_mask:0xf bank_mask:0xf bound_ctrl:1
	v_add_f32_dpp v103, v103, v103 row_ror:4 row_mask:0xf bank_mask:0xa
	v_add_f32_dpp v103, v83, v83 row_ror:12 row_mask:0xf bank_mask:0x5
	v_add_f32_dpp v104, v104, v104 row_ror:4 row_mask:0xf bank_mask:0xa
	v_add_f32_dpp v12, v12, v12 row_ror:8 row_mask:0xf bank_mask:0xf bound_ctrl:1
	v_pk_fma_f32 v[6:7], v[114:115], v[12:13], v[48:49] op_sel_hi:[1,0,1] neg_lo:[1,0,0] neg_hi:[1,0,0]
	v_pk_fma_f32 v[8:9], v[116:117], v[12:13], v[50:51] op_sel_hi:[1,0,1] neg_lo:[1,0,0] neg_hi:[1,0,0]
	v_pk_mul_f32 v[6:7], v[6:7], v[106:107]
	v_pk_mul_f32 v[8:9], v[8:9], v[108:109]
	ds_read_b128 v[36:39], v10 offset:25856
	ds_read_b128 v[44:47], v10 offset:26368
	ds_read_b128 v[40:43], v10 offset:26112
	s_waitcnt lgkmcnt(3)
	v_fma_mix_f32 v12, v6, v20, v180 op_sel_hi:[0,1,0]
	v_fma_mix_f32 v12, v7, v20, v12 op_sel:[0,1,0] op_sel_hi:[0,1,0]
	v_fma_mix_f32 v12, v8, v21, v12 op_sel_hi:[0,1,0]
	v_fma_mix_f32 v12, v9, v21, v12 op_sel:[0,1,0] op_sel_hi:[0,1,0]
	v_fma_mix_f32 v129, v6, v112, v180 op_sel_hi:[0,1,0]
	v_fma_mix_f32 v129, v7, v112, v129 op_sel:[0,1,0] op_sel_hi:[0,1,0]
	v_add_f32_dpp v12, v12, v12 row_ror:1 row_mask:0xf bank_mask:0xf bound_ctrl:1
	v_fma_mix_f32 v129, v8, v113, v129 op_sel_hi:[0,1,0]
	v_fma_mix_f32 v129, v9, v113, v129 op_sel:[0,1,0] op_sel_hi:[0,1,0]
	v_add_f32_dpp v12, v12, v12 row_ror:2 row_mask:0xf bank_mask:0xf bound_ctrl:1
	v_pk_fma_f32 v[48:49], v[28:29], v[66:67], v[6:7] op_sel_hi:[1,0,1]
	v_pk_fma_f32 v[50:51], v[30:31], v[66:67], v[8:9] op_sel_hi:[1,0,1]
	v_add_f32_dpp v12, v12, v12 row_ror:4 row_mask:0xf bank_mask:0xf bound_ctrl:1
	v_add_f32_dpp v104, v100, v100 row_ror:12 row_mask:0xf bank_mask:0x5
	v_add_f32_dpp v105, v105, v105 row_ror:4 row_mask:0xf bank_mask:0xa
	v_add_f32_dpp v105, v101, v101 row_ror:12 row_mask:0xf bank_mask:0x5
	v_add_f32_dpp v12, v12, v12 row_ror:8 row_mask:0xf bank_mask:0xf bound_ctrl:1
	v_pk_fma_f32 v[6:7], v[24:25], v[12:13], v[48:49] op_sel_hi:[1,0,1] neg_lo:[1,0,0] neg_hi:[1,0,0]
	v_pk_fma_f32 v[8:9], v[26:27], v[12:13], v[50:51] op_sel_hi:[1,0,1] neg_lo:[1,0,0] neg_hi:[1,0,0]
	ds_read_b128 v[88:91], v10 offset:26880
	ds_read_b128 v[96:99], v10 offset:27392
	ds_read_b128 v[92:95], v10 offset:27136
	s_waitcnt lgkmcnt(3)
	v_fma_mix_f32 v12, v6, v36, v180 op_sel_hi:[0,1,0]
	v_fma_mix_f32 v12, v7, v36, v12 op_sel:[0,1,0] op_sel_hi:[0,1,0]
	v_fma_mix_f32 v12, v8, v37, v12 op_sel_hi:[0,1,0]
	v_fma_mix_f32 v12, v9, v37, v12 op_sel:[0,1,0] op_sel_hi:[0,1,0]
	v_fma_mix_f32 v130, v6, v22, v180 op_sel_hi:[0,1,0]
	v_fma_mix_f32 v130, v7, v22, v130 op_sel:[0,1,0] op_sel_hi:[0,1,0]
	v_add_f32_dpp v12, v12, v12 row_ror:1 row_mask:0xf bank_mask:0xf bound_ctrl:1
	v_fma_mix_f32 v130, v8, v23, v130 op_sel_hi:[0,1,0]
	v_fma_mix_f32 v130, v9, v23, v130 op_sel:[0,1,0] op_sel_hi:[0,1,0]
	v_add_f32_dpp v12, v12, v12 row_ror:2 row_mask:0xf bank_mask:0xf bound_ctrl:1
	v_pk_fma_f32 v[48:49], v[44:45], v[66:67], v[6:7] op_sel:[0,1,0]
	v_pk_fma_f32 v[50:51], v[46:47], v[66:67], v[8:9] op_sel:[0,1,0]
	v_add_f32_dpp v12, v12, v12 row_ror:4 row_mask:0xf bank_mask:0xf bound_ctrl:1
	v_add_f32_dpp v61, v61, v61 row_ror:4 row_mask:0xf bank_mask:0xa
	v_add_f32_dpp v61, v102, v102 row_ror:12 row_mask:0xf bank_mask:0x5
	v_add_f32_dpp v12, v12, v12 row_ror:8 row_mask:0xf bank_mask:0xf bound_ctrl:1
	v_pk_fma_f32 v[6:7], v[40:41], v[12:13], v[48:49] op_sel_hi:[1,0,1] neg_lo:[1,0,0] neg_hi:[1,0,0]
	v_pk_fma_f32 v[8:9], v[42:43], v[12:13], v[50:51] op_sel_hi:[1,0,1] neg_lo:[1,0,0] neg_hi:[1,0,0]
	ds_read_b128 v[110:113], v10 offset:27904
	ds_read_b128 v[106:109], v10 offset:27648
	ds_read_b128 v[118:121], v10 offset:28416
	ds_read_b128 v[114:117], v10 offset:28160
	ds_read_b128 v[70:73], v11 offset:1792
	s_waitcnt lgkmcnt(5)
	v_fma_mix_f32 v12, v6, v88, v180 op_sel_hi:[0,1,0]
	v_fma_mix_f32 v12, v7, v88, v12 op_sel:[0,1,0] op_sel_hi:[0,1,0]
	v_fma_mix_f32 v12, v8, v89, v12 op_sel_hi:[0,1,0]
	v_fma_mix_f32 v12, v9, v89, v12 op_sel:[0,1,0] op_sel_hi:[0,1,0]
	v_fma_mix_f32 v131, v6, v38, v180 op_sel_hi:[0,1,0]
	v_fma_mix_f32 v131, v7, v38, v131 op_sel:[0,1,0] op_sel_hi:[0,1,0]
	v_add_f32_dpp v12, v12, v12 row_ror:1 row_mask:0xf bank_mask:0xf bound_ctrl:1
	v_fma_mix_f32 v131, v8, v39, v131 op_sel_hi:[0,1,0]
	v_fma_mix_f32 v131, v9, v39, v131 op_sel:[0,1,0] op_sel_hi:[0,1,0]
	v_add_f32_dpp v12, v12, v12 row_ror:2 row_mask:0xf bank_mask:0xf bound_ctrl:1
	v_pk_fma_f32 v[48:49], v[96:97], v[68:69], v[6:7] op_sel_hi:[1,0,1]
	v_pk_fma_f32 v[50:51], v[98:99], v[68:69], v[8:9] op_sel_hi:[1,0,1]
	v_add_f32_dpp v12, v12, v12 row_ror:4 row_mask:0xf bank_mask:0xf bound_ctrl:1
	v_cndmask_b32_e64 v62, v105, v103, s[38:39]
	v_cndmask_b32_e64 v63, v103, v105, s[38:39]
	v_add_f32_dpp v12, v12, v12 row_ror:8 row_mask:0xf bank_mask:0xf bound_ctrl:1
	v_pk_fma_f32 v[6:7], v[92:93], v[12:13], v[48:49] op_sel_hi:[1,0,1] neg_lo:[1,0,0] neg_hi:[1,0,0]
	v_pk_fma_f32 v[8:9], v[94:95], v[12:13], v[50:51] op_sel_hi:[1,0,1] neg_lo:[1,0,0] neg_hi:[1,0,0]
	ds_read_b128 v[20:23], v10 offset:28928
	ds_read_b128 v[28:31], v10 offset:29440
	ds_read_b128 v[24:27], v10 offset:29184
	s_waitcnt lgkmcnt(4)
	v_fma_mix_f32 v12, v6, v110, v180 op_sel_hi:[0,1,0]
	v_fma_mix_f32 v12, v7, v110, v12 op_sel:[0,1,0] op_sel_hi:[0,1,0]
	v_fma_mix_f32 v12, v8, v111, v12 op_sel_hi:[0,1,0]
	v_fma_mix_f32 v12, v9, v111, v12 op_sel:[0,1,0] op_sel_hi:[0,1,0]
	v_fma_mix_f32 v132, v6, v90, v180 op_sel_hi:[0,1,0]
	v_fma_mix_f32 v132, v7, v90, v132 op_sel:[0,1,0] op_sel_hi:[0,1,0]
	v_add_f32_dpp v12, v12, v12 row_ror:1 row_mask:0xf bank_mask:0xf bound_ctrl:1
	v_fma_mix_f32 v132, v8, v91, v132 op_sel_hi:[0,1,0]
	v_fma_mix_f32 v132, v9, v91, v132 op_sel:[0,1,0] op_sel_hi:[0,1,0]
	v_add_f32_dpp v12, v12, v12 row_ror:2 row_mask:0xf bank_mask:0xf bound_ctrl:1
	v_pk_fma_f32 v[48:49], v[118:119], v[68:69], v[6:7] op_sel:[0,1,0]
	v_pk_fma_f32 v[50:51], v[120:121], v[68:69], v[8:9] op_sel:[0,1,0]
	v_add_f32_dpp v12, v12, v12 row_ror:4 row_mask:0xf bank_mask:0xf bound_ctrl:1
	v_cndmask_b32_e64 v64, v61, v104, s[38:39]
	v_cndmask_b32_e64 v65, v104, v61, s[38:39]
	v_add_f32_dpp v12, v12, v12 row_ror:8 row_mask:0xf bank_mask:0xf bound_ctrl:1
	v_pk_fma_f32 v[6:7], v[114:115], v[12:13], v[48:49] op_sel_hi:[1,0,1] neg_lo:[1,0,0] neg_hi:[1,0,0]
	v_pk_fma_f32 v[8:9], v[116:117], v[12:13], v[50:51] op_sel_hi:[1,0,1] neg_lo:[1,0,0] neg_hi:[1,0,0]
	v_pk_mul_f32 v[6:7], v[6:7], v[106:107]
	v_pk_mul_f32 v[8:9], v[8:9], v[108:109]
	ds_read_b128 v[36:39], v10 offset:29952
	ds_read_b128 v[44:47], v10 offset:30464
	ds_read_b128 v[40:43], v10 offset:30208
	s_waitcnt lgkmcnt(3)
	v_fma_mix_f32 v12, v6, v20, v180 op_sel_hi:[0,1,0]
	v_fma_mix_f32 v12, v7, v20, v12 op_sel:[0,1,0] op_sel_hi:[0,1,0]
	v_fma_mix_f32 v12, v8, v21, v12 op_sel_hi:[0,1,0]
	v_fma_mix_f32 v12, v9, v21, v12 op_sel:[0,1,0] op_sel_hi:[0,1,0]
	v_fma_mix_f32 v133, v6, v112, v180 op_sel_hi:[0,1,0]
	v_fma_mix_f32 v133, v7, v112, v133 op_sel:[0,1,0] op_sel_hi:[0,1,0]
	v_add_f32_dpp v12, v12, v12 row_ror:1 row_mask:0xf bank_mask:0xf bound_ctrl:1
	v_fma_mix_f32 v133, v8, v113, v133 op_sel_hi:[0,1,0]
	v_fma_mix_f32 v133, v9, v113, v133 op_sel:[0,1,0] op_sel_hi:[0,1,0]
	v_add_f32_dpp v12, v12, v12 row_ror:2 row_mask:0xf bank_mask:0xf bound_ctrl:1
	v_pk_fma_f32 v[48:49], v[28:29], v[70:71], v[6:7] op_sel_hi:[1,0,1]
	v_pk_fma_f32 v[50:51], v[30:31], v[70:71], v[8:9] op_sel_hi:[1,0,1]
	v_add_f32_dpp v12, v12, v12 row_ror:4 row_mask:0xf bank_mask:0xf bound_ctrl:1
	v_add_f32_dpp v62, v63, v62 quad_perm:[2,3,0,1] row_mask:0xf bank_mask:0xf bound_ctrl:1
	v_add_f32_dpp v63, v65, v64 quad_perm:[2,3,0,1] row_mask:0xf bank_mask:0xf bound_ctrl:1
	v_add_f32_dpp v12, v12, v12 row_ror:8 row_mask:0xf bank_mask:0xf bound_ctrl:1
	v_pk_fma_f32 v[6:7], v[24:25], v[12:13], v[48:49] op_sel_hi:[1,0,1] neg_lo:[1,0,0] neg_hi:[1,0,0]
	v_pk_fma_f32 v[8:9], v[26:27], v[12:13], v[50:51] op_sel_hi:[1,0,1] neg_lo:[1,0,0] neg_hi:[1,0,0]
	ds_read_b128 v[88:91], v10 offset:30976
	ds_read_b128 v[96:99], v10 offset:31488
	ds_read_b128 v[92:95], v10 offset:31232
	s_waitcnt lgkmcnt(3)
	v_fma_mix_f32 v12, v6, v36, v180 op_sel_hi:[0,1,0]
	v_fma_mix_f32 v12, v7, v36, v12 op_sel:[0,1,0] op_sel_hi:[0,1,0]
	v_fma_mix_f32 v12, v8, v37, v12 op_sel_hi:[0,1,0]
	v_fma_mix_f32 v12, v9, v37, v12 op_sel:[0,1,0] op_sel_hi:[0,1,0]
	v_fma_mix_f32 v134, v6, v22, v180 op_sel_hi:[0,1,0]
	v_fma_mix_f32 v134, v7, v22, v134 op_sel:[0,1,0] op_sel_hi:[0,1,0]
	v_add_f32_dpp v12, v12, v12 row_ror:1 row_mask:0xf bank_mask:0xf bound_ctrl:1
	v_fma_mix_f32 v134, v8, v23, v134 op_sel_hi:[0,1,0]
	v_fma_mix_f32 v134, v9, v23, v134 op_sel:[0,1,0] op_sel_hi:[0,1,0]
	v_add_f32_dpp v12, v12, v12 row_ror:2 row_mask:0xf bank_mask:0xf bound_ctrl:1
	v_pk_fma_f32 v[48:49], v[44:45], v[70:71], v[6:7] op_sel:[0,1,0]
	v_pk_fma_f32 v[50:51], v[46:47], v[70:71], v[8:9] op_sel:[0,1,0]
	v_add_f32_dpp v12, v12, v12 row_ror:4 row_mask:0xf bank_mask:0xf bound_ctrl:1
	v_cndmask_b32_e64 v65, v63, v62, s[40:41]
	v_cndmask_b32_e64 v62, v62, v63, s[40:41]
	v_add_f32_dpp v12, v12, v12 row_ror:8 row_mask:0xf bank_mask:0xf bound_ctrl:1
	v_pk_fma_f32 v[6:7], v[40:41], v[12:13], v[48:49] op_sel_hi:[1,0,1] neg_lo:[1,0,0] neg_hi:[1,0,0]
	v_pk_fma_f32 v[8:9], v[42:43], v[12:13], v[50:51] op_sel_hi:[1,0,1] neg_lo:[1,0,0] neg_hi:[1,0,0]
	ds_read_b128 v[110:113], v10 offset:32000
	ds_read_b128 v[106:109], v10 offset:31744
	ds_read_b128 v[118:121], v10 offset:32512
	ds_read_b128 v[114:117], v10 offset:32256
	ds_read_b128 v[66:69], v11 offset:2048
	s_waitcnt lgkmcnt(5)
	v_fma_mix_f32 v12, v6, v88, v180 op_sel_hi:[0,1,0]
	v_fma_mix_f32 v12, v7, v88, v12 op_sel:[0,1,0] op_sel_hi:[0,1,0]
	v_fma_mix_f32 v12, v8, v89, v12 op_sel_hi:[0,1,0]
	v_fma_mix_f32 v12, v9, v89, v12 op_sel:[0,1,0] op_sel_hi:[0,1,0]
	v_fma_mix_f32 v135, v6, v38, v180 op_sel_hi:[0,1,0]
	v_fma_mix_f32 v135, v7, v38, v135 op_sel:[0,1,0] op_sel_hi:[0,1,0]
	v_add_f32_dpp v12, v12, v12 row_ror:1 row_mask:0xf bank_mask:0xf bound_ctrl:1
	v_fma_mix_f32 v135, v8, v39, v135 op_sel_hi:[0,1,0]
	v_fma_mix_f32 v135, v9, v39, v135 op_sel:[0,1,0] op_sel_hi:[0,1,0]
	v_add_f32_dpp v12, v12, v12 row_ror:2 row_mask:0xf bank_mask:0xf bound_ctrl:1
	v_pk_fma_f32 v[48:49], v[96:97], v[72:73], v[6:7] op_sel_hi:[1,0,1]
	v_pk_fma_f32 v[50:51], v[98:99], v[72:73], v[8:9] op_sel_hi:[1,0,1]
	v_add_f32_dpp v12, v12, v12 row_ror:4 row_mask:0xf bank_mask:0xf bound_ctrl:1
	v_add_f32_dpp v62, v62, v65 quad_perm:[1,0,3,2] row_mask:0xf bank_mask:0xf bound_ctrl:1
	v_cvt_pk_bf16_f32 v62, v62, v62
	v_add_f32_dpp v12, v12, v12 row_ror:8 row_mask:0xf bank_mask:0xf bound_ctrl:1
	v_pk_fma_f32 v[6:7], v[92:93], v[12:13], v[48:49] op_sel_hi:[1,0,1] neg_lo:[1,0,0] neg_hi:[1,0,0]
	v_pk_fma_f32 v[8:9], v[94:95], v[12:13], v[50:51] op_sel_hi:[1,0,1] neg_lo:[1,0,0] neg_hi:[1,0,0]
	ds_read_b128 v[20:23], v10 offset:33024
	ds_read_b128 v[28:31], v10 offset:33536
	ds_read_b128 v[24:27], v10 offset:33280
	s_waitcnt lgkmcnt(4)
	v_fma_mix_f32 v12, v6, v110, v180 op_sel_hi:[0,1,0]
	v_fma_mix_f32 v12, v7, v110, v12 op_sel:[0,1,0] op_sel_hi:[0,1,0]
	v_fma_mix_f32 v12, v8, v111, v12 op_sel_hi:[0,1,0]
	v_fma_mix_f32 v12, v9, v111, v12 op_sel:[0,1,0] op_sel_hi:[0,1,0]
	v_fma_mix_f32 v136, v6, v90, v180 op_sel_hi:[0,1,0]
	v_fma_mix_f32 v136, v7, v90, v136 op_sel:[0,1,0] op_sel_hi:[0,1,0]
	v_add_f32_dpp v12, v12, v12 row_ror:1 row_mask:0xf bank_mask:0xf bound_ctrl:1
	v_fma_mix_f32 v136, v8, v91, v136 op_sel_hi:[0,1,0]
	v_fma_mix_f32 v136, v9, v91, v136 op_sel:[0,1,0] op_sel_hi:[0,1,0]
	v_add_f32_dpp v12, v12, v12 row_ror:2 row_mask:0xf bank_mask:0xf bound_ctrl:1
	v_pk_fma_f32 v[48:49], v[118:119], v[72:73], v[6:7] op_sel:[0,1,0]
	v_pk_fma_f32 v[50:51], v[120:121], v[72:73], v[8:9] op_sel:[0,1,0]
	v_add_f32_dpp v12, v12, v12 row_ror:4 row_mask:0xf bank_mask:0xf bound_ctrl:1
	global_store_short v[2:3], v62, off
	v_lshl_add_u64 v[2:3], v[2:3], 0, s[84:85]
	v_add_f32_dpp v12, v12, v12 row_ror:8 row_mask:0xf bank_mask:0xf bound_ctrl:1
	v_pk_fma_f32 v[6:7], v[114:115], v[12:13], v[48:49] op_sel_hi:[1,0,1] neg_lo:[1,0,0] neg_hi:[1,0,0]
	v_pk_fma_f32 v[8:9], v[116:117], v[12:13], v[50:51] op_sel_hi:[1,0,1] neg_lo:[1,0,0] neg_hi:[1,0,0]
	v_pk_mul_f32 v[6:7], v[6:7], v[106:107]
	v_pk_mul_f32 v[8:9], v[8:9], v[108:109]
	ds_read_b128 v[36:39], v10 offset:34048
	ds_read_b128 v[44:47], v10 offset:34560
	ds_read_b128 v[40:43], v10 offset:34304
	s_waitcnt lgkmcnt(3)
	v_fma_mix_f32 v12, v6, v20, v180 op_sel_hi:[0,1,0]
	v_fma_mix_f32 v12, v7, v20, v12 op_sel:[0,1,0] op_sel_hi:[0,1,0]
	v_fma_mix_f32 v12, v8, v21, v12 op_sel_hi:[0,1,0]
	v_fma_mix_f32 v12, v9, v21, v12 op_sel:[0,1,0] op_sel_hi:[0,1,0]
	v_fma_mix_f32 v137, v6, v112, v180 op_sel_hi:[0,1,0]
	v_fma_mix_f32 v137, v7, v112, v137 op_sel:[0,1,0] op_sel_hi:[0,1,0]
	v_add_f32_dpp v12, v12, v12 row_ror:1 row_mask:0xf bank_mask:0xf bound_ctrl:1
	v_fma_mix_f32 v137, v8, v113, v137 op_sel_hi:[0,1,0]
	v_fma_mix_f32 v137, v9, v113, v137 op_sel:[0,1,0] op_sel_hi:[0,1,0]
	v_add_f32_dpp v12, v12, v12 row_ror:2 row_mask:0xf bank_mask:0xf bound_ctrl:1
	v_pk_fma_f32 v[48:49], v[28:29], v[66:67], v[6:7] op_sel_hi:[1,0,1]
	v_pk_fma_f32 v[50:51], v[30:31], v[66:67], v[8:9] op_sel_hi:[1,0,1]
	v_add_f32_dpp v12, v12, v12 row_ror:4 row_mask:0xf bank_mask:0xf bound_ctrl:1
	s_nop 1
	v_add_f32_dpp v12, v12, v12 row_ror:8 row_mask:0xf bank_mask:0xf bound_ctrl:1
	v_pk_fma_f32 v[6:7], v[24:25], v[12:13], v[48:49] op_sel_hi:[1,0,1] neg_lo:[1,0,0] neg_hi:[1,0,0]
	v_pk_fma_f32 v[8:9], v[26:27], v[12:13], v[50:51] op_sel_hi:[1,0,1] neg_lo:[1,0,0] neg_hi:[1,0,0]
	ds_read_b128 v[88:91], v10 offset:35072
	ds_read_b128 v[96:99], v10 offset:35584
	ds_read_b128 v[92:95], v10 offset:35328
	s_waitcnt lgkmcnt(3)
	v_fma_mix_f32 v12, v6, v36, v180 op_sel_hi:[0,1,0]
	v_fma_mix_f32 v12, v7, v36, v12 op_sel:[0,1,0] op_sel_hi:[0,1,0]
	v_fma_mix_f32 v12, v8, v37, v12 op_sel_hi:[0,1,0]
	v_fma_mix_f32 v12, v9, v37, v12 op_sel:[0,1,0] op_sel_hi:[0,1,0]
	v_fma_mix_f32 v52, v6, v22, v180 op_sel_hi:[0,1,0]
	v_fma_mix_f32 v52, v7, v22, v52 op_sel:[0,1,0] op_sel_hi:[0,1,0]
	v_add_f32_dpp v12, v12, v12 row_ror:1 row_mask:0xf bank_mask:0xf bound_ctrl:1
	v_fma_mix_f32 v52, v8, v23, v52 op_sel_hi:[0,1,0]
	v_fma_mix_f32 v52, v9, v23, v52 op_sel:[0,1,0] op_sel_hi:[0,1,0]
	v_add_f32_dpp v12, v12, v12 row_ror:2 row_mask:0xf bank_mask:0xf bound_ctrl:1
	v_pk_fma_f32 v[48:49], v[44:45], v[66:67], v[6:7] op_sel:[0,1,0]
	v_pk_fma_f32 v[50:51], v[46:47], v[66:67], v[8:9] op_sel:[0,1,0]
	v_add_f32_dpp v12, v12, v12 row_ror:4 row_mask:0xf bank_mask:0xf bound_ctrl:1
	v_add_f32_dpp v130, v130, v130 row_ror:8 row_mask:0xf bank_mask:0xc
	v_add_f32_dpp v130, v122, v122 row_ror:8 row_mask:0xf bank_mask:0x3
	v_add_f32_dpp v131, v131, v131 row_ror:8 row_mask:0xf bank_mask:0xc
	v_add_f32_dpp v12, v12, v12 row_ror:8 row_mask:0xf bank_mask:0xf bound_ctrl:1
	v_pk_fma_f32 v[6:7], v[40:41], v[12:13], v[48:49] op_sel_hi:[1,0,1] neg_lo:[1,0,0] neg_hi:[1,0,0]
	v_pk_fma_f32 v[8:9], v[42:43], v[12:13], v[50:51] op_sel_hi:[1,0,1] neg_lo:[1,0,0] neg_hi:[1,0,0]
	ds_read_b128 v[110:113], v10 offset:36096
	ds_read_b128 v[106:109], v10 offset:35840
	ds_read_b128 v[118:121], v10 offset:36608
	ds_read_b128 v[114:117], v10 offset:36352
	ds_read_b128 v[70:73], v11 offset:2304
	s_waitcnt lgkmcnt(5)
	v_fma_mix_f32 v12, v6, v88, v180 op_sel_hi:[0,1,0]
	v_fma_mix_f32 v12, v7, v88, v12 op_sel:[0,1,0] op_sel_hi:[0,1,0]
	v_fma_mix_f32 v12, v8, v89, v12 op_sel_hi:[0,1,0]
	v_fma_mix_f32 v12, v9, v89, v12 op_sel:[0,1,0] op_sel_hi:[0,1,0]
	v_fma_mix_f32 v53, v6, v38, v180 op_sel_hi:[0,1,0]
	v_fma_mix_f32 v53, v7, v38, v53 op_sel:[0,1,0] op_sel_hi:[0,1,0]
	v_add_f32_dpp v12, v12, v12 row_ror:1 row_mask:0xf bank_mask:0xf bound_ctrl:1
	v_fma_mix_f32 v53, v8, v39, v53 op_sel_hi:[0,1,0]
	v_fma_mix_f32 v53, v9, v39, v53 op_sel:[0,1,0] op_sel_hi:[0,1,0]
	v_add_f32_dpp v12, v12, v12 row_ror:2 row_mask:0xf bank_mask:0xf bound_ctrl:1
	v_pk_fma_f32 v[48:49], v[96:97], v[68:69], v[6:7] op_sel_hi:[1,0,1]
	v_pk_fma_f32 v[50:51], v[98:99], v[68:69], v[8:9] op_sel_hi:[1,0,1]
	v_add_f32_dpp v12, v12, v12 row_ror:4 row_mask:0xf bank_mask:0xf bound_ctrl:1
	v_add_f32_dpp v131, v123, v123 row_ror:8 row_mask:0xf bank_mask:0x3
	v_add_f32_dpp v132, v132, v132 row_ror:8 row_mask:0xf bank_mask:0xc
	v_add_f32_dpp v132, v124, v124 row_ror:8 row_mask:0xf bank_mask:0x3
	v_add_f32_dpp v12, v12, v12 row_ror:8 row_mask:0xf bank_mask:0xf bound_ctrl:1
	v_pk_fma_f32 v[6:7], v[92:93], v[12:13], v[48:49] op_sel_hi:[1,0,1] neg_lo:[1,0,0] neg_hi:[1,0,0]
	v_pk_fma_f32 v[8:9], v[94:95], v[12:13], v[50:51] op_sel_hi:[1,0,1] neg_lo:[1,0,0] neg_hi:[1,0,0]
	ds_read_b128 v[20:23], v10 offset:37120
	ds_read_b128 v[28:31], v10 offset:37632
	ds_read_b128 v[24:27], v10 offset:37376
	s_waitcnt lgkmcnt(4)
	v_fma_mix_f32 v12, v6, v110, v180 op_sel_hi:[0,1,0]
	v_fma_mix_f32 v12, v7, v110, v12 op_sel:[0,1,0] op_sel_hi:[0,1,0]
	v_fma_mix_f32 v12, v8, v111, v12 op_sel_hi:[0,1,0]
	v_fma_mix_f32 v12, v9, v111, v12 op_sel:[0,1,0] op_sel_hi:[0,1,0]
	v_fma_mix_f32 v54, v6, v90, v180 op_sel_hi:[0,1,0]
	v_fma_mix_f32 v54, v7, v90, v54 op_sel:[0,1,0] op_sel_hi:[0,1,0]
	v_add_f32_dpp v12, v12, v12 row_ror:1 row_mask:0xf bank_mask:0xf bound_ctrl:1
	v_fma_mix_f32 v54, v8, v91, v54 op_sel_hi:[0,1,0]
	v_fma_mix_f32 v54, v9, v91, v54 op_sel:[0,1,0] op_sel_hi:[0,1,0]
	v_add_f32_dpp v12, v12, v12 row_ror:2 row_mask:0xf bank_mask:0xf bound_ctrl:1
	v_pk_fma_f32 v[48:49], v[118:119], v[68:69], v[6:7] op_sel:[0,1,0]
	v_pk_fma_f32 v[50:51], v[120:121], v[68:69], v[8:9] op_sel:[0,1,0]
	v_add_f32_dpp v12, v12, v12 row_ror:4 row_mask:0xf bank_mask:0xf bound_ctrl:1
	v_add_f32_dpp v133, v133, v133 row_ror:8 row_mask:0xf bank_mask:0xc
	v_add_f32_dpp v133, v125, v125 row_ror:8 row_mask:0xf bank_mask:0x3
	v_add_f32_dpp v134, v134, v134 row_ror:8 row_mask:0xf bank_mask:0xc
	v_add_f32_dpp v12, v12, v12 row_ror:8 row_mask:0xf bank_mask:0xf bound_ctrl:1
	v_pk_fma_f32 v[6:7], v[114:115], v[12:13], v[48:49] op_sel_hi:[1,0,1] neg_lo:[1,0,0] neg_hi:[1,0,0]
	v_pk_fma_f32 v[8:9], v[116:117], v[12:13], v[50:51] op_sel_hi:[1,0,1] neg_lo:[1,0,0] neg_hi:[1,0,0]
	v_pk_mul_f32 v[6:7], v[6:7], v[106:107]
	v_pk_mul_f32 v[8:9], v[8:9], v[108:109]
	ds_read_b128 v[36:39], v10 offset:38144
	ds_read_b128 v[44:47], v10 offset:38656
	ds_read_b128 v[40:43], v10 offset:38400
	s_waitcnt lgkmcnt(3)
	v_fma_mix_f32 v12, v6, v20, v180 op_sel_hi:[0,1,0]
	v_fma_mix_f32 v12, v7, v20, v12 op_sel:[0,1,0] op_sel_hi:[0,1,0]
	v_fma_mix_f32 v12, v8, v21, v12 op_sel_hi:[0,1,0]
	v_fma_mix_f32 v12, v9, v21, v12 op_sel:[0,1,0] op_sel_hi:[0,1,0]
	v_fma_mix_f32 v55, v6, v112, v180 op_sel_hi:[0,1,0]
	v_fma_mix_f32 v55, v7, v112, v55 op_sel:[0,1,0] op_sel_hi:[0,1,0]
	v_add_f32_dpp v12, v12, v12 row_ror:1 row_mask:0xf bank_mask:0xf bound_ctrl:1
	v_fma_mix_f32 v55, v8, v113, v55 op_sel_hi:[0,1,0]
	v_fma_mix_f32 v55, v9, v113, v55 op_sel:[0,1,0] op_sel_hi:[0,1,0]
	v_add_f32_dpp v12, v12, v12 row_ror:2 row_mask:0xf bank_mask:0xf bound_ctrl:1
	v_pk_fma_f32 v[48:49], v[28:29], v[70:71], v[6:7] op_sel_hi:[1,0,1]
	v_pk_fma_f32 v[50:51], v[30:31], v[70:71], v[8:9] op_sel_hi:[1,0,1]
	v_add_f32_dpp v12, v12, v12 row_ror:4 row_mask:0xf bank_mask:0xf bound_ctrl:1
	v_add_f32_dpp v134, v126, v126 row_ror:8 row_mask:0xf bank_mask:0x3
	v_add_f32_dpp v135, v135, v135 row_ror:8 row_mask:0xf bank_mask:0xc
	v_add_f32_dpp v135, v127, v127 row_ror:8 row_mask:0xf bank_mask:0x3
	v_add_f32_dpp v12, v12, v12 row_ror:8 row_mask:0xf bank_mask:0xf bound_ctrl:1
	v_pk_fma_f32 v[6:7], v[24:25], v[12:13], v[48:49] op_sel_hi:[1,0,1] neg_lo:[1,0,0] neg_hi:[1,0,0]
	v_pk_fma_f32 v[8:9], v[26:27], v[12:13], v[50:51] op_sel_hi:[1,0,1] neg_lo:[1,0,0] neg_hi:[1,0,0]
	ds_read_b128 v[88:91], v10 offset:39168
	ds_read_b128 v[96:99], v10 offset:39680
	ds_read_b128 v[92:95], v10 offset:39424
	s_waitcnt lgkmcnt(3)
	v_fma_mix_f32 v12, v6, v36, v180 op_sel_hi:[0,1,0]
	v_fma_mix_f32 v12, v7, v36, v12 op_sel:[0,1,0] op_sel_hi:[0,1,0]
	v_fma_mix_f32 v12, v8, v37, v12 op_sel_hi:[0,1,0]
	v_fma_mix_f32 v12, v9, v37, v12 op_sel:[0,1,0] op_sel_hi:[0,1,0]
	v_fma_mix_f32 v56, v6, v22, v180 op_sel_hi:[0,1,0]
	v_fma_mix_f32 v56, v7, v22, v56 op_sel:[0,1,0] op_sel_hi:[0,1,0]
	v_add_f32_dpp v12, v12, v12 row_ror:1 row_mask:0xf bank_mask:0xf bound_ctrl:1
	v_fma_mix_f32 v56, v8, v23, v56 op_sel_hi:[0,1,0]
	v_fma_mix_f32 v56, v9, v23, v56 op_sel:[0,1,0] op_sel_hi:[0,1,0]
	v_add_f32_dpp v12, v12, v12 row_ror:2 row_mask:0xf bank_mask:0xf bound_ctrl:1
	v_pk_fma_f32 v[48:49], v[44:45], v[70:71], v[6:7] op_sel:[0,1,0]
	v_pk_fma_f32 v[50:51], v[46:47], v[70:71], v[8:9] op_sel:[0,1,0]
	v_add_f32_dpp v12, v12, v12 row_ror:4 row_mask:0xf bank_mask:0xf bound_ctrl:1
	v_add_f32_dpp v136, v136, v136 row_ror:8 row_mask:0xf bank_mask:0xc
	v_add_f32_dpp v136, v128, v128 row_ror:8 row_mask:0xf bank_mask:0x3
	v_add_f32_dpp v12, v12, v12 row_ror:8 row_mask:0xf bank_mask:0xf bound_ctrl:1
	v_pk_fma_f32 v[6:7], v[40:41], v[12:13], v[48:49] op_sel_hi:[1,0,1] neg_lo:[1,0,0] neg_hi:[1,0,0]
	v_pk_fma_f32 v[8:9], v[42:43], v[12:13], v[50:51] op_sel_hi:[1,0,1] neg_lo:[1,0,0] neg_hi:[1,0,0]
	ds_read_b128 v[110:113], v10 offset:40192
	ds_read_b128 v[106:109], v10 offset:39936
	ds_read_b128 v[118:121], v10 offset:40704
	ds_read_b128 v[114:117], v10 offset:40448
	ds_read_b128 v[66:69], v11 offset:2560
	s_waitcnt lgkmcnt(5)
	v_fma_mix_f32 v12, v6, v88, v180 op_sel_hi:[0,1,0]
	v_fma_mix_f32 v12, v7, v88, v12 op_sel:[0,1,0] op_sel_hi:[0,1,0]
	v_fma_mix_f32 v12, v8, v89, v12 op_sel_hi:[0,1,0]
	v_fma_mix_f32 v12, v9, v89, v12 op_sel:[0,1,0] op_sel_hi:[0,1,0]
	v_fma_mix_f32 v57, v6, v38, v180 op_sel_hi:[0,1,0]
	v_fma_mix_f32 v57, v7, v38, v57 op_sel:[0,1,0] op_sel_hi:[0,1,0]
	v_add_f32_dpp v12, v12, v12 row_ror:1 row_mask:0xf bank_mask:0xf bound_ctrl:1
	v_fma_mix_f32 v57, v8, v39, v57 op_sel_hi:[0,1,0]
	v_fma_mix_f32 v57, v9, v39, v57 op_sel:[0,1,0] op_sel_hi:[0,1,0]
	v_add_f32_dpp v12, v12, v12 row_ror:2 row_mask:0xf bank_mask:0xf bound_ctrl:1
	v_pk_fma_f32 v[48:49], v[96:97], v[72:73], v[6:7] op_sel_hi:[1,0,1]
	v_pk_fma_f32 v[50:51], v[98:99], v[72:73], v[8:9] op_sel_hi:[1,0,1]
	v_add_f32_dpp v12, v12, v12 row_ror:4 row_mask:0xf bank_mask:0xf bound_ctrl:1
	v_add_f32_dpp v137, v137, v137 row_ror:8 row_mask:0xf bank_mask:0xc
	v_add_f32_dpp v137, v129, v129 row_ror:8 row_mask:0xf bank_mask:0x3
	v_add_f32_dpp v12, v12, v12 row_ror:8 row_mask:0xf bank_mask:0xf bound_ctrl:1
	v_pk_fma_f32 v[6:7], v[92:93], v[12:13], v[48:49] op_sel_hi:[1,0,1] neg_lo:[1,0,0] neg_hi:[1,0,0]
	v_pk_fma_f32 v[8:9], v[94:95], v[12:13], v[50:51] op_sel_hi:[1,0,1] neg_lo:[1,0,0] neg_hi:[1,0,0]
	ds_read_b128 v[20:23], v10 offset:41216
	ds_read_b128 v[28:31], v10 offset:41728
	ds_read_b128 v[24:27], v10 offset:41472
	s_waitcnt lgkmcnt(4)
	v_fma_mix_f32 v12, v6, v110, v180 op_sel_hi:[0,1,0]
	v_fma_mix_f32 v12, v7, v110, v12 op_sel:[0,1,0] op_sel_hi:[0,1,0]
	v_fma_mix_f32 v12, v8, v111, v12 op_sel_hi:[0,1,0]
	v_fma_mix_f32 v12, v9, v111, v12 op_sel:[0,1,0] op_sel_hi:[0,1,0]
	v_fma_mix_f32 v81, v6, v90, v180 op_sel_hi:[0,1,0]
	v_fma_mix_f32 v81, v7, v90, v81 op_sel:[0,1,0] op_sel_hi:[0,1,0]
	v_add_f32_dpp v12, v12, v12 row_ror:1 row_mask:0xf bank_mask:0xf bound_ctrl:1
	v_fma_mix_f32 v81, v8, v91, v81 op_sel_hi:[0,1,0]
	v_fma_mix_f32 v81, v9, v91, v81 op_sel:[0,1,0] op_sel_hi:[0,1,0]
	v_add_f32_dpp v12, v12, v12 row_ror:2 row_mask:0xf bank_mask:0xf bound_ctrl:1
	v_pk_fma_f32 v[48:49], v[118:119], v[72:73], v[6:7] op_sel:[0,1,0]
	v_pk_fma_f32 v[50:51], v[120:121], v[72:73], v[8:9] op_sel:[0,1,0]
	v_add_f32_dpp v12, v12, v12 row_ror:4 row_mask:0xf bank_mask:0xf bound_ctrl:1
	v_add_f32_dpp v134, v134, v134 row_ror:4 row_mask:0xf bank_mask:0xa
	v_add_f32_dpp v134, v130, v130 row_ror:12 row_mask:0xf bank_mask:0x5
	v_add_f32_dpp v135, v135, v135 row_ror:4 row_mask:0xf bank_mask:0xa
	v_add_f32_dpp v12, v12, v12 row_ror:8 row_mask:0xf bank_mask:0xf bound_ctrl:1
	v_pk_fma_f32 v[6:7], v[114:115], v[12:13], v[48:49] op_sel_hi:[1,0,1] neg_lo:[1,0,0] neg_hi:[1,0,0]
	v_pk_fma_f32 v[8:9], v[116:117], v[12:13], v[50:51] op_sel_hi:[1,0,1] neg_lo:[1,0,0] neg_hi:[1,0,0]
	v_pk_mul_f32 v[6:7], v[6:7], v[106:107]
	v_pk_mul_f32 v[8:9], v[8:9], v[108:109]
	ds_read_b128 v[36:39], v10 offset:42240
	ds_read_b128 v[44:47], v10 offset:42752
	ds_read_b128 v[40:43], v10 offset:42496
	s_waitcnt lgkmcnt(3)
	v_fma_mix_f32 v12, v6, v20, v180 op_sel_hi:[0,1,0]
	v_fma_mix_f32 v12, v7, v20, v12 op_sel:[0,1,0] op_sel_hi:[0,1,0]
	v_fma_mix_f32 v12, v8, v21, v12 op_sel_hi:[0,1,0]
	v_fma_mix_f32 v12, v9, v21, v12 op_sel:[0,1,0] op_sel_hi:[0,1,0]
	v_fma_mix_f32 v82, v6, v112, v180 op_sel_hi:[0,1,0]
	v_fma_mix_f32 v82, v7, v112, v82 op_sel:[0,1,0] op_sel_hi:[0,1,0]
	v_add_f32_dpp v12, v12, v12 row_ror:1 row_mask:0xf bank_mask:0xf bound_ctrl:1
	v_fma_mix_f32 v82, v8, v113, v82 op_sel_hi:[0,1,0]
	v_fma_mix_f32 v82, v9, v113, v82 op_sel:[0,1,0] op_sel_hi:[0,1,0]
	v_add_f32_dpp v12, v12, v12 row_ror:2 row_mask:0xf bank_mask:0xf bound_ctrl:1
	v_pk_fma_f32 v[48:49], v[28:29], v[66:67], v[6:7] op_sel_hi:[1,0,1]
	v_pk_fma_f32 v[50:51], v[30:31], v[66:67], v[8:9] op_sel_hi:[1,0,1]
	v_add_f32_dpp v12, v12, v12 row_ror:4 row_mask:0xf bank_mask:0xf bound_ctrl:1
	v_add_f32_dpp v135, v131, v131 row_ror:12 row_mask:0xf bank_mask:0x5
	v_add_f32_dpp v136, v136, v136 row_ror:4 row_mask:0xf bank_mask:0xa
	v_add_f32_dpp v136, v132, v132 row_ror:12 row_mask:0xf bank_mask:0x5
	v_add_f32_dpp v12, v12, v12 row_ror:8 row_mask:0xf bank_mask:0xf bound_ctrl:1
	v_pk_fma_f32 v[6:7], v[24:25], v[12:13], v[48:49] op_sel_hi:[1,0,1] neg_lo:[1,0,0] neg_hi:[1,0,0]
	v_pk_fma_f32 v[8:9], v[26:27], v[12:13], v[50:51] op_sel_hi:[1,0,1] neg_lo:[1,0,0] neg_hi:[1,0,0]
	ds_read_b128 v[88:91], v10 offset:43264
	ds_read_b128 v[96:99], v10 offset:43776
	ds_read_b128 v[92:95], v10 offset:43520
	s_waitcnt lgkmcnt(3)
	v_fma_mix_f32 v12, v6, v36, v180 op_sel_hi:[0,1,0]
	v_fma_mix_f32 v12, v7, v36, v12 op_sel:[0,1,0] op_sel_hi:[0,1,0]
	v_fma_mix_f32 v12, v8, v37, v12 op_sel_hi:[0,1,0]
	v_fma_mix_f32 v12, v9, v37, v12 op_sel:[0,1,0] op_sel_hi:[0,1,0]
	v_fma_mix_f32 v83, v6, v22, v180 op_sel_hi:[0,1,0]
	v_fma_mix_f32 v83, v7, v22, v83 op_sel:[0,1,0] op_sel_hi:[0,1,0]
	v_add_f32_dpp v12, v12, v12 row_ror:1 row_mask:0xf bank_mask:0xf bound_ctrl:1
	v_fma_mix_f32 v83, v8, v23, v83 op_sel_hi:[0,1,0]
	v_fma_mix_f32 v83, v9, v23, v83 op_sel:[0,1,0] op_sel_hi:[0,1,0]
	v_add_f32_dpp v12, v12, v12 row_ror:2 row_mask:0xf bank_mask:0xf bound_ctrl:1
	v_pk_fma_f32 v[48:49], v[44:45], v[66:67], v[6:7] op_sel:[0,1,0]
	v_pk_fma_f32 v[50:51], v[46:47], v[66:67], v[8:9] op_sel:[0,1,0]
	v_add_f32_dpp v12, v12, v12 row_ror:4 row_mask:0xf bank_mask:0xf bound_ctrl:1
	v_add_f32_dpp v137, v137, v137 row_ror:4 row_mask:0xf bank_mask:0xa
	v_add_f32_dpp v137, v133, v133 row_ror:12 row_mask:0xf bank_mask:0x5
	v_add_f32_dpp v12, v12, v12 row_ror:8 row_mask:0xf bank_mask:0xf bound_ctrl:1
	v_pk_fma_f32 v[6:7], v[40:41], v[12:13], v[48:49] op_sel_hi:[1,0,1] neg_lo:[1,0,0] neg_hi:[1,0,0]
	v_pk_fma_f32 v[8:9], v[42:43], v[12:13], v[50:51] op_sel_hi:[1,0,1] neg_lo:[1,0,0] neg_hi:[1,0,0]
	ds_read_b128 v[110:113], v10 offset:44288
	ds_read_b128 v[106:109], v10 offset:44032
	ds_read_b128 v[118:121], v10 offset:44800
	ds_read_b128 v[114:117], v10 offset:44544
	ds_read_b128 v[70:73], v11 offset:2816
	s_waitcnt lgkmcnt(5)
	v_fma_mix_f32 v12, v6, v88, v180 op_sel_hi:[0,1,0]
	v_fma_mix_f32 v12, v7, v88, v12 op_sel:[0,1,0] op_sel_hi:[0,1,0]
	v_fma_mix_f32 v12, v8, v89, v12 op_sel_hi:[0,1,0]
	v_fma_mix_f32 v12, v9, v89, v12 op_sel:[0,1,0] op_sel_hi:[0,1,0]
	v_fma_mix_f32 v100, v6, v38, v180 op_sel_hi:[0,1,0]
	v_fma_mix_f32 v100, v7, v38, v100 op_sel:[0,1,0] op_sel_hi:[0,1,0]
	v_add_f32_dpp v12, v12, v12 row_ror:1 row_mask:0xf bank_mask:0xf bound_ctrl:1
	v_fma_mix_f32 v100, v8, v39, v100 op_sel_hi:[0,1,0]
	v_fma_mix_f32 v100, v9, v39, v100 op_sel:[0,1,0] op_sel_hi:[0,1,0]
	v_add_f32_dpp v12, v12, v12 row_ror:2 row_mask:0xf bank_mask:0xf bound_ctrl:1
	v_pk_fma_f32 v[48:49], v[96:97], v[68:69], v[6:7] op_sel_hi:[1,0,1]
	v_pk_fma_f32 v[50:51], v[98:99], v[68:69], v[8:9] op_sel_hi:[1,0,1]
	v_add_f32_dpp v12, v12, v12 row_ror:4 row_mask:0xf bank_mask:0xf bound_ctrl:1
	v_cndmask_b32_e64 v62, v136, v134, s[38:39]
	v_cndmask_b32_e64 v63, v134, v136, s[38:39]
	v_add_f32_dpp v12, v12, v12 row_ror:8 row_mask:0xf bank_mask:0xf bound_ctrl:1
	v_pk_fma_f32 v[6:7], v[92:93], v[12:13], v[48:49] op_sel_hi:[1,0,1] neg_lo:[1,0,0] neg_hi:[1,0,0]
	v_pk_fma_f32 v[8:9], v[94:95], v[12:13], v[50:51] op_sel_hi:[1,0,1] neg_lo:[1,0,0] neg_hi:[1,0,0]
	ds_read_b128 v[20:23], v10 offset:45312
	ds_read_b128 v[28:31], v10 offset:45824
	ds_read_b128 v[24:27], v10 offset:45568
	s_waitcnt lgkmcnt(4)
	v_fma_mix_f32 v12, v6, v110, v180 op_sel_hi:[0,1,0]
	v_fma_mix_f32 v12, v7, v110, v12 op_sel:[0,1,0] op_sel_hi:[0,1,0]
	v_fma_mix_f32 v12, v8, v111, v12 op_sel_hi:[0,1,0]
	v_fma_mix_f32 v12, v9, v111, v12 op_sel:[0,1,0] op_sel_hi:[0,1,0]
	v_fma_mix_f32 v101, v6, v90, v180 op_sel_hi:[0,1,0]
	v_fma_mix_f32 v101, v7, v90, v101 op_sel:[0,1,0] op_sel_hi:[0,1,0]
	v_add_f32_dpp v12, v12, v12 row_ror:1 row_mask:0xf bank_mask:0xf bound_ctrl:1
	v_fma_mix_f32 v101, v8, v91, v101 op_sel_hi:[0,1,0]
	v_fma_mix_f32 v101, v9, v91, v101 op_sel:[0,1,0] op_sel_hi:[0,1,0]
	v_add_f32_dpp v12, v12, v12 row_ror:2 row_mask:0xf bank_mask:0xf bound_ctrl:1
	v_pk_fma_f32 v[48:49], v[118:119], v[68:69], v[6:7] op_sel:[0,1,0]
	v_pk_fma_f32 v[50:51], v[120:121], v[68:69], v[8:9] op_sel:[0,1,0]
	v_add_f32_dpp v12, v12, v12 row_ror:4 row_mask:0xf bank_mask:0xf bound_ctrl:1
	v_cndmask_b32_e64 v64, v137, v135, s[38:39]
	v_cndmask_b32_e64 v65, v135, v137, s[38:39]
	v_add_f32_dpp v12, v12, v12 row_ror:8 row_mask:0xf bank_mask:0xf bound_ctrl:1
	v_pk_fma_f32 v[6:7], v[114:115], v[12:13], v[48:49] op_sel_hi:[1,0,1] neg_lo:[1,0,0] neg_hi:[1,0,0]
	v_pk_fma_f32 v[8:9], v[116:117], v[12:13], v[50:51] op_sel_hi:[1,0,1] neg_lo:[1,0,0] neg_hi:[1,0,0]
	v_pk_mul_f32 v[6:7], v[6:7], v[106:107]
	v_pk_mul_f32 v[8:9], v[8:9], v[108:109]
	ds_read_b128 v[36:39], v10 offset:46336
	ds_read_b128 v[44:47], v10 offset:46848
	ds_read_b128 v[40:43], v10 offset:46592
	s_waitcnt lgkmcnt(3)
	v_fma_mix_f32 v12, v6, v20, v180 op_sel_hi:[0,1,0]
	v_fma_mix_f32 v12, v7, v20, v12 op_sel:[0,1,0] op_sel_hi:[0,1,0]
	v_fma_mix_f32 v12, v8, v21, v12 op_sel_hi:[0,1,0]
	v_fma_mix_f32 v12, v9, v21, v12 op_sel:[0,1,0] op_sel_hi:[0,1,0]
	v_fma_mix_f32 v102, v6, v112, v180 op_sel_hi:[0,1,0]
	v_fma_mix_f32 v102, v7, v112, v102 op_sel:[0,1,0] op_sel_hi:[0,1,0]
	v_add_f32_dpp v12, v12, v12 row_ror:1 row_mask:0xf bank_mask:0xf bound_ctrl:1
	v_fma_mix_f32 v102, v8, v113, v102 op_sel_hi:[0,1,0]
	v_fma_mix_f32 v102, v9, v113, v102 op_sel:[0,1,0] op_sel_hi:[0,1,0]
	v_add_f32_dpp v12, v12, v12 row_ror:2 row_mask:0xf bank_mask:0xf bound_ctrl:1
	v_pk_fma_f32 v[48:49], v[28:29], v[70:71], v[6:7] op_sel_hi:[1,0,1]
	v_pk_fma_f32 v[50:51], v[30:31], v[70:71], v[8:9] op_sel_hi:[1,0,1]
	v_add_f32_dpp v12, v12, v12 row_ror:4 row_mask:0xf bank_mask:0xf bound_ctrl:1
	v_add_f32_dpp v62, v63, v62 quad_perm:[2,3,0,1] row_mask:0xf bank_mask:0xf bound_ctrl:1
	v_add_f32_dpp v63, v65, v64 quad_perm:[2,3,0,1] row_mask:0xf bank_mask:0xf bound_ctrl:1
	v_add_f32_dpp v12, v12, v12 row_ror:8 row_mask:0xf bank_mask:0xf bound_ctrl:1
	v_pk_fma_f32 v[6:7], v[24:25], v[12:13], v[48:49] op_sel_hi:[1,0,1] neg_lo:[1,0,0] neg_hi:[1,0,0]
	v_pk_fma_f32 v[8:9], v[26:27], v[12:13], v[50:51] op_sel_hi:[1,0,1] neg_lo:[1,0,0] neg_hi:[1,0,0]
	ds_read_b128 v[88:91], v10 offset:47360
	ds_read_b128 v[96:99], v10 offset:47872
	ds_read_b128 v[92:95], v10 offset:47616
	s_waitcnt lgkmcnt(3)
	v_fma_mix_f32 v12, v6, v36, v180 op_sel_hi:[0,1,0]
	v_fma_mix_f32 v12, v7, v36, v12 op_sel:[0,1,0] op_sel_hi:[0,1,0]
	v_fma_mix_f32 v12, v8, v37, v12 op_sel_hi:[0,1,0]
	v_fma_mix_f32 v12, v9, v37, v12 op_sel:[0,1,0] op_sel_hi:[0,1,0]
	v_fma_mix_f32 v103, v6, v22, v180 op_sel_hi:[0,1,0]
	v_fma_mix_f32 v103, v7, v22, v103 op_sel:[0,1,0] op_sel_hi:[0,1,0]
	v_add_f32_dpp v12, v12, v12 row_ror:1 row_mask:0xf bank_mask:0xf bound_ctrl:1
	v_fma_mix_f32 v103, v8, v23, v103 op_sel_hi:[0,1,0]
	v_fma_mix_f32 v103, v9, v23, v103 op_sel:[0,1,0] op_sel_hi:[0,1,0]
	v_add_f32_dpp v12, v12, v12 row_ror:2 row_mask:0xf bank_mask:0xf bound_ctrl:1
	v_pk_fma_f32 v[48:49], v[44:45], v[70:71], v[6:7] op_sel:[0,1,0]
	v_pk_fma_f32 v[50:51], v[46:47], v[70:71], v[8:9] op_sel:[0,1,0]
	v_add_f32_dpp v12, v12, v12 row_ror:4 row_mask:0xf bank_mask:0xf bound_ctrl:1
	v_cndmask_b32_e64 v65, v63, v62, s[40:41]
	v_cndmask_b32_e64 v62, v62, v63, s[40:41]
	v_add_f32_dpp v12, v12, v12 row_ror:8 row_mask:0xf bank_mask:0xf bound_ctrl:1
	v_pk_fma_f32 v[6:7], v[40:41], v[12:13], v[48:49] op_sel_hi:[1,0,1] neg_lo:[1,0,0] neg_hi:[1,0,0]
	v_pk_fma_f32 v[8:9], v[42:43], v[12:13], v[50:51] op_sel_hi:[1,0,1] neg_lo:[1,0,0] neg_hi:[1,0,0]
	ds_read_b128 v[110:113], v10 offset:48384
	ds_read_b128 v[106:109], v10 offset:48128
	ds_read_b128 v[118:121], v10 offset:48896
	ds_read_b128 v[114:117], v10 offset:48640
	ds_read_b128 v[66:69], v11 offset:3072
	s_waitcnt lgkmcnt(5)
	v_fma_mix_f32 v12, v6, v88, v180 op_sel_hi:[0,1,0]
	v_fma_mix_f32 v12, v7, v88, v12 op_sel:[0,1,0] op_sel_hi:[0,1,0]
	v_fma_mix_f32 v12, v8, v89, v12 op_sel_hi:[0,1,0]
	v_fma_mix_f32 v12, v9, v89, v12 op_sel:[0,1,0] op_sel_hi:[0,1,0]
	v_fma_mix_f32 v104, v6, v38, v180 op_sel_hi:[0,1,0]
	v_fma_mix_f32 v104, v7, v38, v104 op_sel:[0,1,0] op_sel_hi:[0,1,0]
	v_add_f32_dpp v12, v12, v12 row_ror:1 row_mask:0xf bank_mask:0xf bound_ctrl:1
	v_fma_mix_f32 v104, v8, v39, v104 op_sel_hi:[0,1,0]
	v_fma_mix_f32 v104, v9, v39, v104 op_sel:[0,1,0] op_sel_hi:[0,1,0]
	v_add_f32_dpp v12, v12, v12 row_ror:2 row_mask:0xf bank_mask:0xf bound_ctrl:1
	v_pk_fma_f32 v[48:49], v[96:97], v[72:73], v[6:7] op_sel_hi:[1,0,1]
	v_pk_fma_f32 v[50:51], v[98:99], v[72:73], v[8:9] op_sel_hi:[1,0,1]
	v_add_f32_dpp v12, v12, v12 row_ror:4 row_mask:0xf bank_mask:0xf bound_ctrl:1
	v_add_f32_dpp v62, v62, v65 quad_perm:[1,0,3,2] row_mask:0xf bank_mask:0xf bound_ctrl:1
	v_cvt_pk_bf16_f32 v62, v62, v62
	v_add_f32_dpp v12, v12, v12 row_ror:8 row_mask:0xf bank_mask:0xf bound_ctrl:1
	v_pk_fma_f32 v[6:7], v[92:93], v[12:13], v[48:49] op_sel_hi:[1,0,1] neg_lo:[1,0,0] neg_hi:[1,0,0]
	v_pk_fma_f32 v[8:9], v[94:95], v[12:13], v[50:51] op_sel_hi:[1,0,1] neg_lo:[1,0,0] neg_hi:[1,0,0]
	ds_read_b128 v[20:23], v10 offset:49408
	ds_read_b128 v[28:31], v10 offset:49920
	ds_read_b128 v[24:27], v10 offset:49664
	s_waitcnt lgkmcnt(4)
	v_fma_mix_f32 v12, v6, v110, v180 op_sel_hi:[0,1,0]
	v_fma_mix_f32 v12, v7, v110, v12 op_sel:[0,1,0] op_sel_hi:[0,1,0]
	v_fma_mix_f32 v12, v8, v111, v12 op_sel_hi:[0,1,0]
	v_fma_mix_f32 v12, v9, v111, v12 op_sel:[0,1,0] op_sel_hi:[0,1,0]
	v_fma_mix_f32 v105, v6, v90, v180 op_sel_hi:[0,1,0]
	v_fma_mix_f32 v105, v7, v90, v105 op_sel:[0,1,0] op_sel_hi:[0,1,0]
	v_add_f32_dpp v12, v12, v12 row_ror:1 row_mask:0xf bank_mask:0xf bound_ctrl:1
	v_fma_mix_f32 v105, v8, v91, v105 op_sel_hi:[0,1,0]
	v_fma_mix_f32 v105, v9, v91, v105 op_sel:[0,1,0] op_sel_hi:[0,1,0]
	v_add_f32_dpp v12, v12, v12 row_ror:2 row_mask:0xf bank_mask:0xf bound_ctrl:1
	v_pk_fma_f32 v[48:49], v[118:119], v[72:73], v[6:7] op_sel:[0,1,0]
	v_pk_fma_f32 v[50:51], v[120:121], v[72:73], v[8:9] op_sel:[0,1,0]
	v_add_f32_dpp v12, v12, v12 row_ror:4 row_mask:0xf bank_mask:0xf bound_ctrl:1
	global_store_short v[2:3], v62, off
	v_lshl_add_u64 v[2:3], v[2:3], 0, s[84:85]
	v_add_f32_dpp v12, v12, v12 row_ror:8 row_mask:0xf bank_mask:0xf bound_ctrl:1
	v_pk_fma_f32 v[6:7], v[114:115], v[12:13], v[48:49] op_sel_hi:[1,0,1] neg_lo:[1,0,0] neg_hi:[1,0,0]
	v_pk_fma_f32 v[8:9], v[116:117], v[12:13], v[50:51] op_sel_hi:[1,0,1] neg_lo:[1,0,0] neg_hi:[1,0,0]
	v_pk_mul_f32 v[6:7], v[6:7], v[106:107]
	v_pk_mul_f32 v[8:9], v[8:9], v[108:109]
	ds_read_b128 v[36:39], v10 offset:50432
	ds_read_b128 v[44:47], v10 offset:50944
	ds_read_b128 v[40:43], v10 offset:50688
	s_waitcnt lgkmcnt(3)
	v_fma_mix_f32 v12, v6, v20, v180 op_sel_hi:[0,1,0]
	v_fma_mix_f32 v12, v7, v20, v12 op_sel:[0,1,0] op_sel_hi:[0,1,0]
	v_fma_mix_f32 v12, v8, v21, v12 op_sel_hi:[0,1,0]
	v_fma_mix_f32 v12, v9, v21, v12 op_sel:[0,1,0] op_sel_hi:[0,1,0]
	v_fma_mix_f32 v61, v6, v112, v180 op_sel_hi:[0,1,0]
	v_fma_mix_f32 v61, v7, v112, v61 op_sel:[0,1,0] op_sel_hi:[0,1,0]
	v_add_f32_dpp v12, v12, v12 row_ror:1 row_mask:0xf bank_mask:0xf bound_ctrl:1
	v_fma_mix_f32 v61, v8, v113, v61 op_sel_hi:[0,1,0]
	v_fma_mix_f32 v61, v9, v113, v61 op_sel:[0,1,0] op_sel_hi:[0,1,0]
	v_add_f32_dpp v12, v12, v12 row_ror:2 row_mask:0xf bank_mask:0xf bound_ctrl:1
	v_pk_fma_f32 v[48:49], v[28:29], v[66:67], v[6:7] op_sel_hi:[1,0,1]
	v_pk_fma_f32 v[50:51], v[30:31], v[66:67], v[8:9] op_sel_hi:[1,0,1]
	v_add_f32_dpp v12, v12, v12 row_ror:4 row_mask:0xf bank_mask:0xf bound_ctrl:1
	s_nop 1
	v_add_f32_dpp v12, v12, v12 row_ror:8 row_mask:0xf bank_mask:0xf bound_ctrl:1
	v_pk_fma_f32 v[6:7], v[24:25], v[12:13], v[48:49] op_sel_hi:[1,0,1] neg_lo:[1,0,0] neg_hi:[1,0,0]
	v_pk_fma_f32 v[8:9], v[26:27], v[12:13], v[50:51] op_sel_hi:[1,0,1] neg_lo:[1,0,0] neg_hi:[1,0,0]
	ds_read_b128 v[88:91], v10 offset:51456
	ds_read_b128 v[96:99], v10 offset:51968
	ds_read_b128 v[92:95], v10 offset:51712
	s_waitcnt lgkmcnt(3)
	v_fma_mix_f32 v12, v6, v36, v180 op_sel_hi:[0,1,0]
	v_fma_mix_f32 v12, v7, v36, v12 op_sel:[0,1,0] op_sel_hi:[0,1,0]
	v_fma_mix_f32 v12, v8, v37, v12 op_sel_hi:[0,1,0]
	v_fma_mix_f32 v12, v9, v37, v12 op_sel:[0,1,0] op_sel_hi:[0,1,0]
	v_fma_mix_f32 v122, v6, v22, v180 op_sel_hi:[0,1,0]
	v_fma_mix_f32 v122, v7, v22, v122 op_sel:[0,1,0] op_sel_hi:[0,1,0]
	v_add_f32_dpp v12, v12, v12 row_ror:1 row_mask:0xf bank_mask:0xf bound_ctrl:1
	v_fma_mix_f32 v122, v8, v23, v122 op_sel_hi:[0,1,0]
	v_fma_mix_f32 v122, v9, v23, v122 op_sel:[0,1,0] op_sel_hi:[0,1,0]
	v_add_f32_dpp v12, v12, v12 row_ror:2 row_mask:0xf bank_mask:0xf bound_ctrl:1
	v_pk_fma_f32 v[48:49], v[44:45], v[66:67], v[6:7] op_sel:[0,1,0]
	v_pk_fma_f32 v[50:51], v[46:47], v[66:67], v[8:9] op_sel:[0,1,0]
	v_add_f32_dpp v12, v12, v12 row_ror:4 row_mask:0xf bank_mask:0xf bound_ctrl:1
	v_add_f32_dpp v83, v83, v83 row_ror:8 row_mask:0xf bank_mask:0xc
	v_add_f32_dpp v83, v52, v52 row_ror:8 row_mask:0xf bank_mask:0x3
	v_add_f32_dpp v100, v100, v100 row_ror:8 row_mask:0xf bank_mask:0xc
	v_add_f32_dpp v12, v12, v12 row_ror:8 row_mask:0xf bank_mask:0xf bound_ctrl:1
	v_pk_fma_f32 v[6:7], v[40:41], v[12:13], v[48:49] op_sel_hi:[1,0,1] neg_lo:[1,0,0] neg_hi:[1,0,0]
	v_pk_fma_f32 v[8:9], v[42:43], v[12:13], v[50:51] op_sel_hi:[1,0,1] neg_lo:[1,0,0] neg_hi:[1,0,0]
	ds_read_b128 v[110:113], v10 offset:52480
	ds_read_b128 v[106:109], v10 offset:52224
	ds_read_b128 v[118:121], v10 offset:52992
	ds_read_b128 v[114:117], v10 offset:52736
	ds_read_b128 v[70:73], v11 offset:3328
	s_waitcnt lgkmcnt(5)
	v_fma_mix_f32 v12, v6, v88, v180 op_sel_hi:[0,1,0]
	v_fma_mix_f32 v12, v7, v88, v12 op_sel:[0,1,0] op_sel_hi:[0,1,0]
	v_fma_mix_f32 v12, v8, v89, v12 op_sel_hi:[0,1,0]
	v_fma_mix_f32 v12, v9, v89, v12 op_sel:[0,1,0] op_sel_hi:[0,1,0]
	v_fma_mix_f32 v123, v6, v38, v180 op_sel_hi:[0,1,0]
	v_fma_mix_f32 v123, v7, v38, v123 op_sel:[0,1,0] op_sel_hi:[0,1,0]
	v_add_f32_dpp v12, v12, v12 row_ror:1 row_mask:0xf bank_mask:0xf bound_ctrl:1
	v_fma_mix_f32 v123, v8, v39, v123 op_sel_hi:[0,1,0]
	v_fma_mix_f32 v123, v9, v39, v123 op_sel:[0,1,0] op_sel_hi:[0,1,0]
	v_add_f32_dpp v12, v12, v12 row_ror:2 row_mask:0xf bank_mask:0xf bound_ctrl:1
	v_pk_fma_f32 v[48:49], v[96:97], v[68:69], v[6:7] op_sel_hi:[1,0,1]
	v_pk_fma_f32 v[50:51], v[98:99], v[68:69], v[8:9] op_sel_hi:[1,0,1]
	v_add_f32_dpp v12, v12, v12 row_ror:4 row_mask:0xf bank_mask:0xf bound_ctrl:1
	v_add_f32_dpp v100, v53, v53 row_ror:8 row_mask:0xf bank_mask:0x3
	v_add_f32_dpp v101, v101, v101 row_ror:8 row_mask:0xf bank_mask:0xc
	v_add_f32_dpp v101, v54, v54 row_ror:8 row_mask:0xf bank_mask:0x3
	v_add_f32_dpp v12, v12, v12 row_ror:8 row_mask:0xf bank_mask:0xf bound_ctrl:1
	v_pk_fma_f32 v[6:7], v[92:93], v[12:13], v[48:49] op_sel_hi:[1,0,1] neg_lo:[1,0,0] neg_hi:[1,0,0]
	v_pk_fma_f32 v[8:9], v[94:95], v[12:13], v[50:51] op_sel_hi:[1,0,1] neg_lo:[1,0,0] neg_hi:[1,0,0]
	ds_read_b128 v[20:23], v10 offset:53504
	ds_read_b128 v[28:31], v10 offset:54016
	ds_read_b128 v[24:27], v10 offset:53760
	s_waitcnt lgkmcnt(4)
	v_fma_mix_f32 v12, v6, v110, v180 op_sel_hi:[0,1,0]
	v_fma_mix_f32 v12, v7, v110, v12 op_sel:[0,1,0] op_sel_hi:[0,1,0]
	v_fma_mix_f32 v12, v8, v111, v12 op_sel_hi:[0,1,0]
	v_fma_mix_f32 v12, v9, v111, v12 op_sel:[0,1,0] op_sel_hi:[0,1,0]
	v_fma_mix_f32 v124, v6, v90, v180 op_sel_hi:[0,1,0]
	v_fma_mix_f32 v124, v7, v90, v124 op_sel:[0,1,0] op_sel_hi:[0,1,0]
	v_add_f32_dpp v12, v12, v12 row_ror:1 row_mask:0xf bank_mask:0xf bound_ctrl:1
	v_fma_mix_f32 v124, v8, v91, v124 op_sel_hi:[0,1,0]
	v_fma_mix_f32 v124, v9, v91, v124 op_sel:[0,1,0] op_sel_hi:[0,1,0]
	v_add_f32_dpp v12, v12, v12 row_ror:2 row_mask:0xf bank_mask:0xf bound_ctrl:1
	v_pk_fma_f32 v[48:49], v[118:119], v[68:69], v[6:7] op_sel:[0,1,0]
	v_pk_fma_f32 v[50:51], v[120:121], v[68:69], v[8:9] op_sel:[0,1,0]
	v_add_f32_dpp v12, v12, v12 row_ror:4 row_mask:0xf bank_mask:0xf bound_ctrl:1
	v_add_f32_dpp v102, v102, v102 row_ror:8 row_mask:0xf bank_mask:0xc
	v_add_f32_dpp v102, v55, v55 row_ror:8 row_mask:0xf bank_mask:0x3
	v_add_f32_dpp v103, v103, v103 row_ror:8 row_mask:0xf bank_mask:0xc
	v_add_f32_dpp v12, v12, v12 row_ror:8 row_mask:0xf bank_mask:0xf bound_ctrl:1
	v_pk_fma_f32 v[6:7], v[114:115], v[12:13], v[48:49] op_sel_hi:[1,0,1] neg_lo:[1,0,0] neg_hi:[1,0,0]
	v_pk_fma_f32 v[8:9], v[116:117], v[12:13], v[50:51] op_sel_hi:[1,0,1] neg_lo:[1,0,0] neg_hi:[1,0,0]
	v_pk_mul_f32 v[6:7], v[6:7], v[106:107]
	v_pk_mul_f32 v[8:9], v[8:9], v[108:109]
	ds_read_b128 v[36:39], v10 offset:54528
	ds_read_b128 v[44:47], v10 offset:55040
	ds_read_b128 v[40:43], v10 offset:54784
	s_waitcnt lgkmcnt(3)
	v_fma_mix_f32 v12, v6, v20, v180 op_sel_hi:[0,1,0]
	v_fma_mix_f32 v12, v7, v20, v12 op_sel:[0,1,0] op_sel_hi:[0,1,0]
	v_fma_mix_f32 v12, v8, v21, v12 op_sel_hi:[0,1,0]
	v_fma_mix_f32 v12, v9, v21, v12 op_sel:[0,1,0] op_sel_hi:[0,1,0]
	v_fma_mix_f32 v125, v6, v112, v180 op_sel_hi:[0,1,0]
	v_fma_mix_f32 v125, v7, v112, v125 op_sel:[0,1,0] op_sel_hi:[0,1,0]
	v_add_f32_dpp v12, v12, v12 row_ror:1 row_mask:0xf bank_mask:0xf bound_ctrl:1
	v_fma_mix_f32 v125, v8, v113, v125 op_sel_hi:[0,1,0]
	v_fma_mix_f32 v125, v9, v113, v125 op_sel:[0,1,0] op_sel_hi:[0,1,0]
	v_add_f32_dpp v12, v12, v12 row_ror:2 row_mask:0xf bank_mask:0xf bound_ctrl:1
	v_pk_fma_f32 v[48:49], v[28:29], v[70:71], v[6:7] op_sel_hi:[1,0,1]
	v_pk_fma_f32 v[50:51], v[30:31], v[70:71], v[8:9] op_sel_hi:[1,0,1]
	v_add_f32_dpp v12, v12, v12 row_ror:4 row_mask:0xf bank_mask:0xf bound_ctrl:1
	v_add_f32_dpp v103, v56, v56 row_ror:8 row_mask:0xf bank_mask:0x3
	v_add_f32_dpp v104, v104, v104 row_ror:8 row_mask:0xf bank_mask:0xc
	v_add_f32_dpp v104, v57, v57 row_ror:8 row_mask:0xf bank_mask:0x3
	v_add_f32_dpp v12, v12, v12 row_ror:8 row_mask:0xf bank_mask:0xf bound_ctrl:1
	v_pk_fma_f32 v[6:7], v[24:25], v[12:13], v[48:49] op_sel_hi:[1,0,1] neg_lo:[1,0,0] neg_hi:[1,0,0]
	v_pk_fma_f32 v[8:9], v[26:27], v[12:13], v[50:51] op_sel_hi:[1,0,1] neg_lo:[1,0,0] neg_hi:[1,0,0]
	ds_read_b128 v[88:91], v10 offset:55552
	ds_read_b128 v[96:99], v10 offset:56064
	ds_read_b128 v[92:95], v10 offset:55808
	s_waitcnt lgkmcnt(3)
	v_fma_mix_f32 v12, v6, v36, v180 op_sel_hi:[0,1,0]
	v_fma_mix_f32 v12, v7, v36, v12 op_sel:[0,1,0] op_sel_hi:[0,1,0]
	v_fma_mix_f32 v12, v8, v37, v12 op_sel_hi:[0,1,0]
	v_fma_mix_f32 v12, v9, v37, v12 op_sel:[0,1,0] op_sel_hi:[0,1,0]
	v_fma_mix_f32 v126, v6, v22, v180 op_sel_hi:[0,1,0]
	v_fma_mix_f32 v126, v7, v22, v126 op_sel:[0,1,0] op_sel_hi:[0,1,0]
	v_add_f32_dpp v12, v12, v12 row_ror:1 row_mask:0xf bank_mask:0xf bound_ctrl:1
	v_fma_mix_f32 v126, v8, v23, v126 op_sel_hi:[0,1,0]
	v_fma_mix_f32 v126, v9, v23, v126 op_sel:[0,1,0] op_sel_hi:[0,1,0]
	v_add_f32_dpp v12, v12, v12 row_ror:2 row_mask:0xf bank_mask:0xf bound_ctrl:1
	v_pk_fma_f32 v[48:49], v[44:45], v[70:71], v[6:7] op_sel:[0,1,0]
	v_pk_fma_f32 v[50:51], v[46:47], v[70:71], v[8:9] op_sel:[0,1,0]
	v_add_f32_dpp v12, v12, v12 row_ror:4 row_mask:0xf bank_mask:0xf bound_ctrl:1
	v_add_f32_dpp v105, v105, v105 row_ror:8 row_mask:0xf bank_mask:0xc
	v_add_f32_dpp v105, v81, v81 row_ror:8 row_mask:0xf bank_mask:0x3
	v_add_f32_dpp v12, v12, v12 row_ror:8 row_mask:0xf bank_mask:0xf bound_ctrl:1
	v_pk_fma_f32 v[6:7], v[40:41], v[12:13], v[48:49] op_sel_hi:[1,0,1] neg_lo:[1,0,0] neg_hi:[1,0,0]
	v_pk_fma_f32 v[8:9], v[42:43], v[12:13], v[50:51] op_sel_hi:[1,0,1] neg_lo:[1,0,0] neg_hi:[1,0,0]
	ds_read_b128 v[110:113], v10 offset:56576
	ds_read_b128 v[106:109], v10 offset:56320
	ds_read_b128 v[118:121], v10 offset:57088
	ds_read_b128 v[114:117], v10 offset:56832
	ds_read_b128 v[66:69], v11 offset:3584
	s_waitcnt lgkmcnt(5)
	v_fma_mix_f32 v12, v6, v88, v180 op_sel_hi:[0,1,0]
	v_fma_mix_f32 v12, v7, v88, v12 op_sel:[0,1,0] op_sel_hi:[0,1,0]
	v_fma_mix_f32 v12, v8, v89, v12 op_sel_hi:[0,1,0]
	v_fma_mix_f32 v12, v9, v89, v12 op_sel:[0,1,0] op_sel_hi:[0,1,0]
	v_fma_mix_f32 v127, v6, v38, v180 op_sel_hi:[0,1,0]
	v_fma_mix_f32 v127, v7, v38, v127 op_sel:[0,1,0] op_sel_hi:[0,1,0]
	v_add_f32_dpp v12, v12, v12 row_ror:1 row_mask:0xf bank_mask:0xf bound_ctrl:1
	v_fma_mix_f32 v127, v8, v39, v127 op_sel_hi:[0,1,0]
	v_fma_mix_f32 v127, v9, v39, v127 op_sel:[0,1,0] op_sel_hi:[0,1,0]
	v_add_f32_dpp v12, v12, v12 row_ror:2 row_mask:0xf bank_mask:0xf bound_ctrl:1
	v_pk_fma_f32 v[48:49], v[96:97], v[72:73], v[6:7] op_sel_hi:[1,0,1]
	v_pk_fma_f32 v[50:51], v[98:99], v[72:73], v[8:9] op_sel_hi:[1,0,1]
	v_add_f32_dpp v12, v12, v12 row_ror:4 row_mask:0xf bank_mask:0xf bound_ctrl:1
	v_add_f32_dpp v61, v61, v61 row_ror:8 row_mask:0xf bank_mask:0xc
	v_add_f32_dpp v61, v82, v82 row_ror:8 row_mask:0xf bank_mask:0x3
	v_add_f32_dpp v12, v12, v12 row_ror:8 row_mask:0xf bank_mask:0xf bound_ctrl:1
	v_pk_fma_f32 v[6:7], v[92:93], v[12:13], v[48:49] op_sel_hi:[1,0,1] neg_lo:[1,0,0] neg_hi:[1,0,0]
	v_pk_fma_f32 v[8:9], v[94:95], v[12:13], v[50:51] op_sel_hi:[1,0,1] neg_lo:[1,0,0] neg_hi:[1,0,0]
	ds_read_b128 v[20:23], v10 offset:57600
	ds_read_b128 v[28:31], v10 offset:58112
	ds_read_b128 v[24:27], v10 offset:57856
	s_waitcnt lgkmcnt(4)
	v_fma_mix_f32 v12, v6, v110, v180 op_sel_hi:[0,1,0]
	v_fma_mix_f32 v12, v7, v110, v12 op_sel:[0,1,0] op_sel_hi:[0,1,0]
	v_fma_mix_f32 v12, v8, v111, v12 op_sel_hi:[0,1,0]
	v_fma_mix_f32 v12, v9, v111, v12 op_sel:[0,1,0] op_sel_hi:[0,1,0]
	v_fma_mix_f32 v128, v6, v90, v180 op_sel_hi:[0,1,0]
	v_fma_mix_f32 v128, v7, v90, v128 op_sel:[0,1,0] op_sel_hi:[0,1,0]
	v_add_f32_dpp v12, v12, v12 row_ror:1 row_mask:0xf bank_mask:0xf bound_ctrl:1
	v_fma_mix_f32 v128, v8, v91, v128 op_sel_hi:[0,1,0]
	v_fma_mix_f32 v128, v9, v91, v128 op_sel:[0,1,0] op_sel_hi:[0,1,0]
	v_add_f32_dpp v12, v12, v12 row_ror:2 row_mask:0xf bank_mask:0xf bound_ctrl:1
	v_pk_fma_f32 v[48:49], v[118:119], v[72:73], v[6:7] op_sel:[0,1,0]
	v_pk_fma_f32 v[50:51], v[120:121], v[72:73], v[8:9] op_sel:[0,1,0]
	v_add_f32_dpp v12, v12, v12 row_ror:4 row_mask:0xf bank_mask:0xf bound_ctrl:1
	v_add_f32_dpp v103, v103, v103 row_ror:4 row_mask:0xf bank_mask:0xa
	v_add_f32_dpp v103, v83, v83 row_ror:12 row_mask:0xf bank_mask:0x5
	v_add_f32_dpp v104, v104, v104 row_ror:4 row_mask:0xf bank_mask:0xa
	v_add_f32_dpp v12, v12, v12 row_ror:8 row_mask:0xf bank_mask:0xf bound_ctrl:1
	v_pk_fma_f32 v[6:7], v[114:115], v[12:13], v[48:49] op_sel_hi:[1,0,1] neg_lo:[1,0,0] neg_hi:[1,0,0]
	v_pk_fma_f32 v[8:9], v[116:117], v[12:13], v[50:51] op_sel_hi:[1,0,1] neg_lo:[1,0,0] neg_hi:[1,0,0]
	v_pk_mul_f32 v[6:7], v[6:7], v[106:107]
	v_pk_mul_f32 v[8:9], v[8:9], v[108:109]
	ds_read_b128 v[36:39], v10 offset:58624
	ds_read_b128 v[44:47], v10 offset:59136
	ds_read_b128 v[40:43], v10 offset:58880
	s_waitcnt lgkmcnt(3)
	v_fma_mix_f32 v12, v6, v20, v180 op_sel_hi:[0,1,0]
	v_fma_mix_f32 v12, v7, v20, v12 op_sel:[0,1,0] op_sel_hi:[0,1,0]
	v_fma_mix_f32 v12, v8, v21, v12 op_sel_hi:[0,1,0]
	v_fma_mix_f32 v12, v9, v21, v12 op_sel:[0,1,0] op_sel_hi:[0,1,0]
	v_fma_mix_f32 v129, v6, v112, v180 op_sel_hi:[0,1,0]
	v_fma_mix_f32 v129, v7, v112, v129 op_sel:[0,1,0] op_sel_hi:[0,1,0]
	v_add_f32_dpp v12, v12, v12 row_ror:1 row_mask:0xf bank_mask:0xf bound_ctrl:1
	v_fma_mix_f32 v129, v8, v113, v129 op_sel_hi:[0,1,0]
	v_fma_mix_f32 v129, v9, v113, v129 op_sel:[0,1,0] op_sel_hi:[0,1,0]
	v_add_f32_dpp v12, v12, v12 row_ror:2 row_mask:0xf bank_mask:0xf bound_ctrl:1
	v_pk_fma_f32 v[48:49], v[28:29], v[66:67], v[6:7] op_sel_hi:[1,0,1]
	v_pk_fma_f32 v[50:51], v[30:31], v[66:67], v[8:9] op_sel_hi:[1,0,1]
	v_add_f32_dpp v12, v12, v12 row_ror:4 row_mask:0xf bank_mask:0xf bound_ctrl:1
	v_add_f32_dpp v104, v100, v100 row_ror:12 row_mask:0xf bank_mask:0x5
	v_add_f32_dpp v105, v105, v105 row_ror:4 row_mask:0xf bank_mask:0xa
	v_add_f32_dpp v105, v101, v101 row_ror:12 row_mask:0xf bank_mask:0x5
	v_add_f32_dpp v12, v12, v12 row_ror:8 row_mask:0xf bank_mask:0xf bound_ctrl:1
	v_pk_fma_f32 v[6:7], v[24:25], v[12:13], v[48:49] op_sel_hi:[1,0,1] neg_lo:[1,0,0] neg_hi:[1,0,0]
	v_pk_fma_f32 v[8:9], v[26:27], v[12:13], v[50:51] op_sel_hi:[1,0,1] neg_lo:[1,0,0] neg_hi:[1,0,0]
	ds_read_b128 v[88:91], v10 offset:59648
	ds_read_b128 v[96:99], v10 offset:60160
	ds_read_b128 v[92:95], v10 offset:59904
	s_waitcnt lgkmcnt(3)
	v_fma_mix_f32 v12, v6, v36, v180 op_sel_hi:[0,1,0]
	v_fma_mix_f32 v12, v7, v36, v12 op_sel:[0,1,0] op_sel_hi:[0,1,0]
	v_fma_mix_f32 v12, v8, v37, v12 op_sel_hi:[0,1,0]
	v_fma_mix_f32 v12, v9, v37, v12 op_sel:[0,1,0] op_sel_hi:[0,1,0]
	v_fma_mix_f32 v130, v6, v22, v180 op_sel_hi:[0,1,0]
	v_fma_mix_f32 v130, v7, v22, v130 op_sel:[0,1,0] op_sel_hi:[0,1,0]
	v_add_f32_dpp v12, v12, v12 row_ror:1 row_mask:0xf bank_mask:0xf bound_ctrl:1
	v_fma_mix_f32 v130, v8, v23, v130 op_sel_hi:[0,1,0]
	v_fma_mix_f32 v130, v9, v23, v130 op_sel:[0,1,0] op_sel_hi:[0,1,0]
	v_add_f32_dpp v12, v12, v12 row_ror:2 row_mask:0xf bank_mask:0xf bound_ctrl:1
	v_pk_fma_f32 v[48:49], v[44:45], v[66:67], v[6:7] op_sel:[0,1,0]
	v_pk_fma_f32 v[50:51], v[46:47], v[66:67], v[8:9] op_sel:[0,1,0]
	v_add_f32_dpp v12, v12, v12 row_ror:4 row_mask:0xf bank_mask:0xf bound_ctrl:1
	v_add_f32_dpp v61, v61, v61 row_ror:4 row_mask:0xf bank_mask:0xa
	v_add_f32_dpp v61, v102, v102 row_ror:12 row_mask:0xf bank_mask:0x5
	v_add_f32_dpp v12, v12, v12 row_ror:8 row_mask:0xf bank_mask:0xf bound_ctrl:1
	v_pk_fma_f32 v[6:7], v[40:41], v[12:13], v[48:49] op_sel_hi:[1,0,1] neg_lo:[1,0,0] neg_hi:[1,0,0]
	v_pk_fma_f32 v[8:9], v[42:43], v[12:13], v[50:51] op_sel_hi:[1,0,1] neg_lo:[1,0,0] neg_hi:[1,0,0]
	ds_read_b128 v[110:113], v10 offset:60672
	ds_read_b128 v[106:109], v10 offset:60416
	ds_read_b128 v[118:121], v10 offset:61184
	ds_read_b128 v[114:117], v10 offset:60928
	ds_read_b128 v[70:73], v11 offset:3840
	s_waitcnt lgkmcnt(5)
	v_fma_mix_f32 v12, v6, v88, v180 op_sel_hi:[0,1,0]
	v_fma_mix_f32 v12, v7, v88, v12 op_sel:[0,1,0] op_sel_hi:[0,1,0]
	v_fma_mix_f32 v12, v8, v89, v12 op_sel_hi:[0,1,0]
	v_fma_mix_f32 v12, v9, v89, v12 op_sel:[0,1,0] op_sel_hi:[0,1,0]
	v_fma_mix_f32 v131, v6, v38, v180 op_sel_hi:[0,1,0]
	v_fma_mix_f32 v131, v7, v38, v131 op_sel:[0,1,0] op_sel_hi:[0,1,0]
	v_add_f32_dpp v12, v12, v12 row_ror:1 row_mask:0xf bank_mask:0xf bound_ctrl:1
	v_fma_mix_f32 v131, v8, v39, v131 op_sel_hi:[0,1,0]
	v_fma_mix_f32 v131, v9, v39, v131 op_sel:[0,1,0] op_sel_hi:[0,1,0]
	v_add_f32_dpp v12, v12, v12 row_ror:2 row_mask:0xf bank_mask:0xf bound_ctrl:1
	v_pk_fma_f32 v[48:49], v[96:97], v[68:69], v[6:7] op_sel_hi:[1,0,1]
	v_pk_fma_f32 v[50:51], v[98:99], v[68:69], v[8:9] op_sel_hi:[1,0,1]
	v_add_f32_dpp v12, v12, v12 row_ror:4 row_mask:0xf bank_mask:0xf bound_ctrl:1
	v_cndmask_b32_e64 v62, v105, v103, s[38:39]
	v_cndmask_b32_e64 v63, v103, v105, s[38:39]
	v_add_f32_dpp v12, v12, v12 row_ror:8 row_mask:0xf bank_mask:0xf bound_ctrl:1
	v_pk_fma_f32 v[6:7], v[92:93], v[12:13], v[48:49] op_sel_hi:[1,0,1] neg_lo:[1,0,0] neg_hi:[1,0,0]
	v_pk_fma_f32 v[8:9], v[94:95], v[12:13], v[50:51] op_sel_hi:[1,0,1] neg_lo:[1,0,0] neg_hi:[1,0,0]
	ds_read_b128 v[20:23], v10 offset:61696
	ds_read_b128 v[28:31], v10 offset:62208
	ds_read_b128 v[24:27], v10 offset:61952
	s_waitcnt lgkmcnt(4)
	v_fma_mix_f32 v12, v6, v110, v180 op_sel_hi:[0,1,0]
	v_fma_mix_f32 v12, v7, v110, v12 op_sel:[0,1,0] op_sel_hi:[0,1,0]
	v_fma_mix_f32 v12, v8, v111, v12 op_sel_hi:[0,1,0]
	v_fma_mix_f32 v12, v9, v111, v12 op_sel:[0,1,0] op_sel_hi:[0,1,0]
	v_fma_mix_f32 v132, v6, v90, v180 op_sel_hi:[0,1,0]
	v_fma_mix_f32 v132, v7, v90, v132 op_sel:[0,1,0] op_sel_hi:[0,1,0]
	v_add_f32_dpp v12, v12, v12 row_ror:1 row_mask:0xf bank_mask:0xf bound_ctrl:1
	v_fma_mix_f32 v132, v8, v91, v132 op_sel_hi:[0,1,0]
	v_fma_mix_f32 v132, v9, v91, v132 op_sel:[0,1,0] op_sel_hi:[0,1,0]
	v_add_f32_dpp v12, v12, v12 row_ror:2 row_mask:0xf bank_mask:0xf bound_ctrl:1
	v_pk_fma_f32 v[48:49], v[118:119], v[68:69], v[6:7] op_sel:[0,1,0]
	v_pk_fma_f32 v[50:51], v[120:121], v[68:69], v[8:9] op_sel:[0,1,0]
	v_add_f32_dpp v12, v12, v12 row_ror:4 row_mask:0xf bank_mask:0xf bound_ctrl:1
	v_cndmask_b32_e64 v64, v61, v104, s[38:39]
	v_cndmask_b32_e64 v65, v104, v61, s[38:39]
	v_add_f32_dpp v12, v12, v12 row_ror:8 row_mask:0xf bank_mask:0xf bound_ctrl:1
	v_pk_fma_f32 v[6:7], v[114:115], v[12:13], v[48:49] op_sel_hi:[1,0,1] neg_lo:[1,0,0] neg_hi:[1,0,0]
	v_pk_fma_f32 v[8:9], v[116:117], v[12:13], v[50:51] op_sel_hi:[1,0,1] neg_lo:[1,0,0] neg_hi:[1,0,0]
	v_pk_mul_f32 v[6:7], v[6:7], v[106:107]
	v_pk_mul_f32 v[8:9], v[8:9], v[108:109]
	ds_read_b128 v[36:39], v10 offset:62720
	ds_read_b128 v[44:47], v10 offset:63232
	ds_read_b128 v[40:43], v10 offset:62976
	s_waitcnt lgkmcnt(3)
	v_fma_mix_f32 v12, v6, v20, v180 op_sel_hi:[0,1,0]
	v_fma_mix_f32 v12, v7, v20, v12 op_sel:[0,1,0] op_sel_hi:[0,1,0]
	v_fma_mix_f32 v12, v8, v21, v12 op_sel_hi:[0,1,0]
	v_fma_mix_f32 v12, v9, v21, v12 op_sel:[0,1,0] op_sel_hi:[0,1,0]
	v_fma_mix_f32 v133, v6, v112, v180 op_sel_hi:[0,1,0]
	v_fma_mix_f32 v133, v7, v112, v133 op_sel:[0,1,0] op_sel_hi:[0,1,0]
	v_add_f32_dpp v12, v12, v12 row_ror:1 row_mask:0xf bank_mask:0xf bound_ctrl:1
	v_fma_mix_f32 v133, v8, v113, v133 op_sel_hi:[0,1,0]
	v_fma_mix_f32 v133, v9, v113, v133 op_sel:[0,1,0] op_sel_hi:[0,1,0]
	v_add_f32_dpp v12, v12, v12 row_ror:2 row_mask:0xf bank_mask:0xf bound_ctrl:1
	v_pk_fma_f32 v[48:49], v[28:29], v[70:71], v[6:7] op_sel_hi:[1,0,1]
	v_pk_fma_f32 v[50:51], v[30:31], v[70:71], v[8:9] op_sel_hi:[1,0,1]
	v_add_f32_dpp v12, v12, v12 row_ror:4 row_mask:0xf bank_mask:0xf bound_ctrl:1
	v_add_f32_dpp v62, v63, v62 quad_perm:[2,3,0,1] row_mask:0xf bank_mask:0xf bound_ctrl:1
	v_add_f32_dpp v63, v65, v64 quad_perm:[2,3,0,1] row_mask:0xf bank_mask:0xf bound_ctrl:1
	v_add_f32_dpp v12, v12, v12 row_ror:8 row_mask:0xf bank_mask:0xf bound_ctrl:1
	v_pk_fma_f32 v[6:7], v[24:25], v[12:13], v[48:49] op_sel_hi:[1,0,1] neg_lo:[1,0,0] neg_hi:[1,0,0]
	v_pk_fma_f32 v[8:9], v[26:27], v[12:13], v[50:51] op_sel_hi:[1,0,1] neg_lo:[1,0,0] neg_hi:[1,0,0]
	ds_read_b128 v[88:91], v10 offset:63744
	ds_read_b128 v[96:99], v10 offset:64256
	ds_read_b128 v[92:95], v10 offset:64000
	s_waitcnt lgkmcnt(3)
	v_fma_mix_f32 v12, v6, v36, v180 op_sel_hi:[0,1,0]
	v_fma_mix_f32 v12, v7, v36, v12 op_sel:[0,1,0] op_sel_hi:[0,1,0]
	v_fma_mix_f32 v12, v8, v37, v12 op_sel_hi:[0,1,0]
	v_fma_mix_f32 v12, v9, v37, v12 op_sel:[0,1,0] op_sel_hi:[0,1,0]
	v_fma_mix_f32 v134, v6, v22, v180 op_sel_hi:[0,1,0]
	v_fma_mix_f32 v134, v7, v22, v134 op_sel:[0,1,0] op_sel_hi:[0,1,0]
	v_add_f32_dpp v12, v12, v12 row_ror:1 row_mask:0xf bank_mask:0xf bound_ctrl:1
	v_fma_mix_f32 v134, v8, v23, v134 op_sel_hi:[0,1,0]
	v_fma_mix_f32 v134, v9, v23, v134 op_sel:[0,1,0] op_sel_hi:[0,1,0]
	v_add_f32_dpp v12, v12, v12 row_ror:2 row_mask:0xf bank_mask:0xf bound_ctrl:1
	v_pk_fma_f32 v[48:49], v[44:45], v[70:71], v[6:7] op_sel:[0,1,0]
	v_pk_fma_f32 v[50:51], v[46:47], v[70:71], v[8:9] op_sel:[0,1,0]
	v_add_f32_dpp v12, v12, v12 row_ror:4 row_mask:0xf bank_mask:0xf bound_ctrl:1
	v_cndmask_b32_e64 v65, v63, v62, s[40:41]
	v_cndmask_b32_e64 v62, v62, v63, s[40:41]
	v_add_f32_dpp v12, v12, v12 row_ror:8 row_mask:0xf bank_mask:0xf bound_ctrl:1
	v_pk_fma_f32 v[6:7], v[40:41], v[12:13], v[48:49] op_sel_hi:[1,0,1] neg_lo:[1,0,0] neg_hi:[1,0,0]
	v_pk_fma_f32 v[8:9], v[42:43], v[12:13], v[50:51] op_sel_hi:[1,0,1] neg_lo:[1,0,0] neg_hi:[1,0,0]
	ds_read_b128 v[110:113], v10 offset:64768
	ds_read_b128 v[106:109], v10 offset:64512
	ds_read_b128 v[118:121], v10 offset:65280
	ds_read_b128 v[114:117], v10 offset:65024
	s_waitcnt lgkmcnt(4)
	v_fma_mix_f32 v12, v6, v88, v180 op_sel_hi:[0,1,0]
	v_fma_mix_f32 v12, v7, v88, v12 op_sel:[0,1,0] op_sel_hi:[0,1,0]
	v_fma_mix_f32 v12, v8, v89, v12 op_sel_hi:[0,1,0]
	v_fma_mix_f32 v12, v9, v89, v12 op_sel:[0,1,0] op_sel_hi:[0,1,0]
	v_fma_mix_f32 v135, v6, v38, v180 op_sel_hi:[0,1,0]
	v_fma_mix_f32 v135, v7, v38, v135 op_sel:[0,1,0] op_sel_hi:[0,1,0]
	v_add_f32_dpp v12, v12, v12 row_ror:1 row_mask:0xf bank_mask:0xf bound_ctrl:1
	v_fma_mix_f32 v135, v8, v39, v135 op_sel_hi:[0,1,0]
	v_fma_mix_f32 v135, v9, v39, v135 op_sel:[0,1,0] op_sel_hi:[0,1,0]
	v_add_f32_dpp v12, v12, v12 row_ror:2 row_mask:0xf bank_mask:0xf bound_ctrl:1
	v_pk_fma_f32 v[48:49], v[96:97], v[72:73], v[6:7] op_sel_hi:[1,0,1]
	v_pk_fma_f32 v[50:51], v[98:99], v[72:73], v[8:9] op_sel_hi:[1,0,1]
	v_add_f32_dpp v12, v12, v12 row_ror:4 row_mask:0xf bank_mask:0xf bound_ctrl:1
	v_add_f32_dpp v62, v62, v65 quad_perm:[1,0,3,2] row_mask:0xf bank_mask:0xf bound_ctrl:1
	v_cvt_pk_bf16_f32 v62, v62, v62
	v_add_f32_dpp v12, v12, v12 row_ror:8 row_mask:0xf bank_mask:0xf bound_ctrl:1
	v_pk_fma_f32 v[6:7], v[92:93], v[12:13], v[48:49] op_sel_hi:[1,0,1] neg_lo:[1,0,0] neg_hi:[1,0,0]
	v_pk_fma_f32 v[8:9], v[94:95], v[12:13], v[50:51] op_sel_hi:[1,0,1] neg_lo:[1,0,0] neg_hi:[1,0,0]
	s_waitcnt lgkmcnt(0)
	s_barrier
	v_xor_b32_e32 v10, 0x10000, v10
	v_xor_b32_e32 v11, 0x1000, v11
	ds_read_b128 v[66:69], v11 offset:0
	ds_read_b128 v[20:23], v10 offset:256
	ds_read_b128 v[28:31], v10 offset:768
	ds_read_b128 v[24:27], v10 offset:512
	ds_read_b128 v[36:39], v10 offset:1280
	ds_read_b128 v[44:47], v10 offset:1792
	ds_read_b128 v[40:43], v10 offset:1536
	v_fma_mix_f32 v12, v6, v110, v180 op_sel_hi:[0,1,0]
	v_fma_mix_f32 v12, v7, v110, v12 op_sel:[0,1,0] op_sel_hi:[0,1,0]
	v_fma_mix_f32 v12, v8, v111, v12 op_sel_hi:[0,1,0]
	v_fma_mix_f32 v12, v9, v111, v12 op_sel:[0,1,0] op_sel_hi:[0,1,0]
	v_fma_mix_f32 v136, v6, v90, v180 op_sel_hi:[0,1,0]
	v_fma_mix_f32 v136, v7, v90, v136 op_sel:[0,1,0] op_sel_hi:[0,1,0]
	v_add_f32_dpp v12, v12, v12 row_ror:1 row_mask:0xf bank_mask:0xf bound_ctrl:1
	v_fma_mix_f32 v136, v8, v91, v136 op_sel_hi:[0,1,0]
	v_fma_mix_f32 v136, v9, v91, v136 op_sel:[0,1,0] op_sel_hi:[0,1,0]
	v_add_f32_dpp v12, v12, v12 row_ror:2 row_mask:0xf bank_mask:0xf bound_ctrl:1
	v_pk_fma_f32 v[48:49], v[118:119], v[72:73], v[6:7] op_sel:[0,1,0]
	v_pk_fma_f32 v[50:51], v[120:121], v[72:73], v[8:9] op_sel:[0,1,0]
	v_add_f32_dpp v12, v12, v12 row_ror:4 row_mask:0xf bank_mask:0xf bound_ctrl:1
	global_store_short v[2:3], v62, off
	v_lshl_add_u64 v[2:3], v[2:3], 0, s[84:85]
	v_add_f32_dpp v12, v12, v12 row_ror:8 row_mask:0xf bank_mask:0xf bound_ctrl:1
	v_pk_fma_f32 v[6:7], v[114:115], v[12:13], v[48:49] op_sel_hi:[1,0,1] neg_lo:[1,0,0] neg_hi:[1,0,0]
	v_pk_fma_f32 v[8:9], v[116:117], v[12:13], v[50:51] op_sel_hi:[1,0,1] neg_lo:[1,0,0] neg_hi:[1,0,0]
	v_pk_mul_f32 v[6:7], v[6:7], v[106:107]
	v_pk_mul_f32 v[8:9], v[8:9], v[108:109]
	v_fma_mix_f32 v137, v6, v112, v180 op_sel_hi:[0,1,0]
	v_fma_mix_f32 v137, v7, v112, v137 op_sel:[0,1,0] op_sel_hi:[0,1,0]
	v_fma_mix_f32 v137, v8, v113, v137 op_sel_hi:[0,1,0]
	v_fma_mix_f32 v137, v9, v113, v137 op_sel:[0,1,0] op_sel_hi:[0,1,0]
	v_mov_b32_e32 v170, v2
	v_mov_b32_e32 v171, v3
	s_mov_b64 s[100:101], -1
	s_cmp_lg_u32 s28, 0x800000
	s_cbranch_scc1 .Lscan_cons_chunk
	v_add_f32_dpp v130, v130, v130 row_ror:8 row_mask:0xf bank_mask:0xc
	v_add_f32_dpp v130, v122, v122 row_ror:8 row_mask:0xf bank_mask:0x3
	v_add_f32_dpp v131, v131, v131 row_ror:8 row_mask:0xf bank_mask:0xc
	v_add_f32_dpp v131, v123, v123 row_ror:8 row_mask:0xf bank_mask:0x3
	v_add_f32_dpp v132, v132, v132 row_ror:8 row_mask:0xf bank_mask:0xc
	v_add_f32_dpp v132, v124, v124 row_ror:8 row_mask:0xf bank_mask:0x3
	v_add_f32_dpp v133, v133, v133 row_ror:8 row_mask:0xf bank_mask:0xc
	v_add_f32_dpp v133, v125, v125 row_ror:8 row_mask:0xf bank_mask:0x3
	v_add_f32_dpp v134, v134, v134 row_ror:8 row_mask:0xf bank_mask:0xc
	v_add_f32_dpp v134, v126, v126 row_ror:8 row_mask:0xf bank_mask:0x3
	v_add_f32_dpp v135, v135, v135 row_ror:8 row_mask:0xf bank_mask:0xc
	v_add_f32_dpp v135, v127, v127 row_ror:8 row_mask:0xf bank_mask:0x3
	v_add_f32_dpp v136, v136, v136 row_ror:8 row_mask:0xf bank_mask:0xc
	v_add_f32_dpp v136, v128, v128 row_ror:8 row_mask:0xf bank_mask:0x3
	v_add_f32_dpp v137, v137, v137 row_ror:8 row_mask:0xf bank_mask:0xc
	v_add_f32_dpp v137, v129, v129 row_ror:8 row_mask:0xf bank_mask:0x3
	v_add_f32_dpp v134, v134, v134 row_ror:4 row_mask:0xf bank_mask:0xa
	v_add_f32_dpp v134, v130, v130 row_ror:12 row_mask:0xf bank_mask:0x5
	v_add_f32_dpp v135, v135, v135 row_ror:4 row_mask:0xf bank_mask:0xa
	v_add_f32_dpp v135, v131, v131 row_ror:12 row_mask:0xf bank_mask:0x5
	v_add_f32_dpp v136, v136, v136 row_ror:4 row_mask:0xf bank_mask:0xa
	v_add_f32_dpp v136, v132, v132 row_ror:12 row_mask:0xf bank_mask:0x5
	v_add_f32_dpp v137, v137, v137 row_ror:4 row_mask:0xf bank_mask:0xa
	v_add_f32_dpp v137, v133, v133 row_ror:12 row_mask:0xf bank_mask:0x5
	v_cndmask_b32_e64 v62, v136, v134, s[38:39]
	v_cndmask_b32_e64 v63, v134, v136, s[38:39]
	v_cndmask_b32_e64 v64, v137, v135, s[38:39]
	v_cndmask_b32_e64 v65, v135, v137, s[38:39]
	v_add_f32_dpp v62, v63, v62 quad_perm:[2,3,0,1] row_mask:0xf bank_mask:0xf bound_ctrl:1
	s_nop 0
	v_add_f32_dpp v63, v65, v64 quad_perm:[2,3,0,1] row_mask:0xf bank_mask:0xf bound_ctrl:1
	v_cndmask_b32_e64 v65, v63, v62, s[40:41]
	v_cndmask_b32_e64 v62, v62, v63, s[40:41]
	s_nop 1
	v_add_f32_dpp v62, v62, v65 quad_perm:[1,0,3,2] row_mask:0xf bank_mask:0xf bound_ctrl:1
	v_cvt_pk_bf16_f32 v62, v62, v62
	global_store_short v[2:3], v62, off
	s_branch .LBB0_53
